# v19 plus snake MFMA order inside each 16-MFMA block (B operand changes 10x instead of 16x per block), 44 K-loop blocks
# speedup vs baseline: 1.0105x; 1.0105x over previous
; #define PG8_STAGE(bufoff, gbase, voff) do { _Pragma("unroll") for (int _i = 0; _i < 2; ++_i) \
;         __builtin_amdgcn_global_load_lds((const unsigned*)((const char*)(gbase) + (voff)[_i]), (PG8_LAS unsigned*)(lds + (bufoff) + ldsw + _i * 8192), 16, 0, 0); } while (0)
; #define PG8_LDA(dst, b, h) do { _Pragma("unroll") for (int m = 0; m < 4; ++m) _Pragma("unroll") for (int k = 0; k < 2; ++k) dst[m][k] = *(const PG8_LAS bf16x8*)(lds + PG8_SA(b, h) + aoff + m * 2048 + k * 1024); } while (0)
; #define PG8_MMA(ai, bj, At, Bt) do { __builtin_amdgcn_s_setprio(1); _Pragma("unroll") for (int m = 0; m < 4; ++m) _Pragma("unroll") for (int n = 0; n < 2; ++n) _Pragma("unroll") for (int k = 0; k < 2; ++k) \
;         acc[ai][bj][m][n] = __builtin_amdgcn_mfma_f32_16x16x32_bf16(Bt[n][k], At[m][k], acc[ai][bj][m][n], 0, 0, 0); __builtin_amdgcn_s_setprio(0); } while (0)
; #define PG8_WAIT_V(n) asm volatile("s_waitcnt vmcnt(" #n ")" ::: "memory")
; #define PG8_WAIT_L(n) asm volatile("s_waitcnt lgkmcnt(" #n ")" ::: "memory")
; #define PG8_BAR __builtin_amdgcn_s_barrier()
; #define PG8_SCHED __builtin_amdgcn_sched_barrier(0)
; template <class Epi, class Sched, bool ALIGN_EPI = false, bool SP2 = false>
; __device__ __forceinline__ void gemm_phase(PG8_LAS unsigned char* lds, const Gemm g, const Sched& S, const Epi& E) {
;     ...
;             PG8_WAIT_V(8); PG8_WAIT_L(0); PG8_BAR; PG8_MMA(0, 0, At, B0); PG8_MMA(0, 1, At, B1); PG8_BAR; PG8_SCHED;
;             PG8_LDA(At, 0, 1); PG8_STAGE(PG8_SB(0, 0), b2, voffB); PG8_STAGE(PG8_SB(0, 1), b2 + hstep, voffB); PG8_STAGE(PG8_SA(0, 0), a2, voffA);
.Lrj_P1_0:
	s_waitcnt lgkmcnt(0)
	s_barrier
	s_setprio 1
	s_waitcnt lgkmcnt(0)
	v_mfma_f32_16x16x32_bf16 v[124:127], v[128:131], v[202:205], v[124:127]
	v_mfma_f32_16x16x32_bf16 v[120:123], v[136:139], v[202:205], v[120:123]
	v_mfma_f32_16x16x32_bf16 v[104:107], v[136:139], v[210:213], v[104:107]
	v_mfma_f32_16x16x32_bf16 v[108:111], v[128:131], v[210:213], v[108:111]
	v_mfma_f32_16x16x32_bf16 v[92:95], v[128:131], v[218:221], v[92:95]
	v_mfma_f32_16x16x32_bf16 v[88:91], v[136:139], v[218:221], v[88:91]
	v_mfma_f32_16x16x32_bf16 v[72:75], v[136:139], v[230:233], v[72:75]
	v_mfma_f32_16x16x32_bf16 v[76:79], v[128:131], v[230:233], v[76:79]
	v_mfma_f32_16x16x32_bf16 v[124:127], v[132:135], v[206:209], v[124:127]
	v_mfma_f32_16x16x32_bf16 v[120:123], v[140:143], v[206:209], v[120:123]
	v_mfma_f32_16x16x32_bf16 v[104:107], v[140:143], v[214:217], v[104:107]
	v_mfma_f32_16x16x32_bf16 v[108:111], v[132:135], v[214:217], v[108:111]
	v_mfma_f32_16x16x32_bf16 v[92:95], v[132:135], v[222:225], v[92:95]
	v_mfma_f32_16x16x32_bf16 v[88:91], v[140:143], v[222:225], v[88:91]
	v_mfma_f32_16x16x32_bf16 v[72:75], v[140:143], v[234:237], v[72:75]
	v_mfma_f32_16x16x32_bf16 v[76:79], v[132:135], v[234:237], v[76:79]
	s_setprio 0
	s_setprio 1
	v_mfma_f32_16x16x32_bf16 v[116:119], v[144:147], v[202:205], v[116:119]
	v_mfma_f32_16x16x32_bf16 v[112:115], v[184:187], v[202:205], v[112:115]
	v_mfma_f32_16x16x32_bf16 v[96:99], v[184:187], v[210:213], v[96:99]
	v_mfma_f32_16x16x32_bf16 v[100:103], v[144:147], v[210:213], v[100:103]
	v_mfma_f32_16x16x32_bf16 v[84:87], v[144:147], v[218:221], v[84:87]
	v_mfma_f32_16x16x32_bf16 v[80:83], v[184:187], v[218:221], v[80:83]
	v_mfma_f32_16x16x32_bf16 v[64:67], v[184:187], v[230:233], v[64:67]
	v_mfma_f32_16x16x32_bf16 v[68:71], v[144:147], v[230:233], v[68:71]
	v_mfma_f32_16x16x32_bf16 v[116:119], v[148:151], v[206:209], v[116:119]
	v_mfma_f32_16x16x32_bf16 v[112:115], v[188:191], v[206:209], v[112:115]
	v_mfma_f32_16x16x32_bf16 v[96:99], v[188:191], v[214:217], v[96:99]
	v_mfma_f32_16x16x32_bf16 v[100:103], v[148:151], v[214:217], v[100:103]
	v_mfma_f32_16x16x32_bf16 v[84:87], v[148:151], v[222:225], v[84:87]
	v_mfma_f32_16x16x32_bf16 v[80:83], v[188:191], v[222:225], v[80:83]
	v_mfma_f32_16x16x32_bf16 v[64:67], v[188:191], v[234:237], v[64:67]
	v_mfma_f32_16x16x32_bf16 v[68:71], v[148:151], v[234:237], v[68:71]
	s_setprio 0
	s_barrier
	s_add_i32 s29, s33, s74
	v_lshl_add_u64 v[192:193], s[6:7], 0, v[158:159]
	s_mov_b32 m0, s29
	ds_read_b128 v[202:205], v194 offset:16384
	ds_read_b128 v[206:209], v194 offset:17408
	ds_read_b128 v[210:213], v194 offset:18432
	ds_read_b128 v[214:217], v194 offset:19456
	ds_read_b128 v[218:221], v194 offset:20480
	ds_read_b128 v[222:225], v194 offset:21504
	ds_read_b128 v[230:233], v194 offset:22528
	ds_read_b128 v[234:237], v194 offset:23552
	global_load_lds_dwordx4 v[192:193], off
	s_add_i32 m0, s29, 0x2000
	s_add_u32 s38, s6, 0x40000
	v_lshl_add_u64 v[238:239], s[6:7], 0, v[162:163]
	s_addc_u32 s39, s7, 0
	s_add_i32 s29, s83, s74
	global_load_lds_dwordx4 v[238:239], off
	v_lshl_add_u64 v[240:241], s[38:39], 0, v[158:159]
	s_mov_b32 m0, s29
	v_lshl_add_u64 v[242:243], s[8:9], 0, v[160:161]
	global_load_lds_dwordx4 v[240:241], off
	v_lshl_add_u64 v[240:241], s[38:39], 0, v[162:163]
	s_add_i32 m0, s29, 0x2000
	s_nop 0
	global_load_lds_dwordx4 v[240:241], off
	v_lshl_add_u64 v[240:241], s[8:9], 0, v[156:157]
	s_mov_b32 m0, s37
	s_nop 0
	global_load_lds_dwordx4 v[240:241], off
	s_mov_b32 m0, s75
	s_nop 0
	global_load_lds_dwordx4 v[242:243], off
	s_cmp_eq_u32 s99, 1
	s_cbranch_scc1 .Lrw_P1_1
	s_waitcnt vmcnt(8)
	s_branch .Lrj_P1_1

; #define PG8_STAGE(bufoff, gbase, voff) do { _Pragma("unroll") for (int _i = 0; _i < 2; ++_i) \
;         __builtin_amdgcn_global_load_lds((const unsigned*)((const char*)(gbase) + (voff)[_i]), (PG8_LAS unsigned*)(lds + (bufoff) + ldsw + _i * 8192), 16, 0, 0); } while (0)
; #define PG8_LDA(dst, b, h) do { _Pragma("unroll") for (int m = 0; m < 4; ++m) _Pragma("unroll") for (int k = 0; k < 2; ++k) dst[m][k] = *(const PG8_LAS bf16x8*)(lds + PG8_SA(b, h) + aoff + m * 2048 + k * 1024); } while (0)
; #define PG8_LDB(dst, b, h) do { _Pragma("unroll") for (int n = 0; n < 2; ++n) _Pragma("unroll") for (int k = 0; k < 2; ++k) dst[n][k] = *(const PG8_LAS bf16x8*)(lds + PG8_SB(b, h) + boff + n * 2048 + k * 1024); } while (0)
; #define PG8_MMA(ai, bj, At, Bt) do { __builtin_amdgcn_s_setprio(1); _Pragma("unroll") for (int m = 0; m < 4; ++m) _Pragma("unroll") for (int n = 0; n < 2; ++n) _Pragma("unroll") for (int k = 0; k < 2; ++k) \
;         acc[ai][bj][m][n] = __builtin_amdgcn_mfma_f32_16x16x32_bf16(Bt[n][k], At[m][k], acc[ai][bj][m][n], 0, 0, 0); __builtin_amdgcn_s_setprio(0); } while (0)
; #define PG8_WAIT_V(n) asm volatile("s_waitcnt vmcnt(" #n ")" ::: "memory")
; #define PG8_WAIT_L(n) asm volatile("s_waitcnt lgkmcnt(" #n ")" ::: "memory")
; #define PG8_BAR __builtin_amdgcn_s_barrier()
; #define PG8_SCHED __builtin_amdgcn_sched_barrier(0)
; template <class Epi, class Sched, bool ALIGN_EPI = false, bool SP2 = false>
; __device__ __forceinline__ void gemm_phase(PG8_LAS unsigned char* lds, const Gemm g, const Sched& S, const Epi& E) {
;     ...
;             PG8_WAIT_V(8); PG8_WAIT_L(0); PG8_BAR; PG8_MMA(0, 0, At, B0); PG8_MMA(0, 1, At, B1); PG8_BAR; PG8_SCHED;
;             PG8_LDA(At, 0, 1); PG8_STAGE(PG8_SB(0, 0), b2, voffB); PG8_STAGE(PG8_SB(0, 1), b2 + hstep, voffB); PG8_STAGE(PG8_SA(0, 0), a2, voffA);
;             PG8_WAIT_V(8); PG8_WAIT_L(0); PG8_BAR; PG8_MMA(1, 0, At, B0); PG8_MMA(1, 1, At, B1); PG8_BAR; PG8_SCHED;
;             PG8_LDB(B0, 1, 0); PG8_LDB(B1, 1, 1); PG8_SCHED; PG8_LDA(At, 1, 0); PG8_STAGE(PG8_SA(0, 1), a2 + hstep, voffA);
;             PG8_WAIT_V(8); PG8_WAIT_L(0); PG8_BAR; PG8_MMA(0, 0, At, B0); PG8_MMA(0, 1, At, B1); PG8_BAR; PG8_SCHED;
.Lrj_P1_1:
	s_waitcnt lgkmcnt(0)
	s_barrier
	s_setprio 1
	s_waitcnt lgkmcnt(0)
	v_mfma_f32_16x16x32_bf16 v[60:63], v[128:131], v[202:205], v[60:63]
	v_mfma_f32_16x16x32_bf16 v[56:59], v[136:139], v[202:205], v[56:59]
	v_mfma_f32_16x16x32_bf16 v[40:43], v[136:139], v[210:213], v[40:43]
	v_mfma_f32_16x16x32_bf16 v[44:47], v[128:131], v[210:213], v[44:47]
	v_mfma_f32_16x16x32_bf16 v[28:31], v[128:131], v[218:221], v[28:31]
	v_mfma_f32_16x16x32_bf16 v[24:27], v[136:139], v[218:221], v[24:27]
	v_mfma_f32_16x16x32_bf16 v[8:11], v[136:139], v[230:233], v[8:11]
	v_mfma_f32_16x16x32_bf16 v[12:15], v[128:131], v[230:233], v[12:15]
	v_mfma_f32_16x16x32_bf16 v[60:63], v[132:135], v[206:209], v[60:63]
	v_mfma_f32_16x16x32_bf16 v[56:59], v[140:143], v[206:209], v[56:59]
	v_mfma_f32_16x16x32_bf16 v[40:43], v[140:143], v[214:217], v[40:43]
	v_mfma_f32_16x16x32_bf16 v[44:47], v[132:135], v[214:217], v[44:47]
	v_mfma_f32_16x16x32_bf16 v[28:31], v[132:135], v[222:225], v[28:31]
	v_mfma_f32_16x16x32_bf16 v[24:27], v[140:143], v[222:225], v[24:27]
	v_mfma_f32_16x16x32_bf16 v[8:11], v[140:143], v[234:237], v[8:11]
	v_mfma_f32_16x16x32_bf16 v[12:15], v[132:135], v[234:237], v[12:15]
	s_setprio 0
	s_setprio 1
	v_mfma_f32_16x16x32_bf16 v[52:55], v[144:147], v[202:205], v[52:55]
	v_mfma_f32_16x16x32_bf16 v[48:51], v[184:187], v[202:205], v[48:51]
	v_mfma_f32_16x16x32_bf16 v[32:35], v[184:187], v[210:213], v[32:35]
	v_mfma_f32_16x16x32_bf16 v[36:39], v[144:147], v[210:213], v[36:39]
	v_mfma_f32_16x16x32_bf16 v[20:23], v[144:147], v[218:221], v[20:23]
	v_mfma_f32_16x16x32_bf16 v[16:19], v[184:187], v[218:221], v[16:19]
	v_mfma_f32_16x16x32_bf16 v[0:3], v[184:187], v[230:233], v[0:3]
	v_mfma_f32_16x16x32_bf16 v[4:7], v[144:147], v[230:233], v[4:7]
	v_mfma_f32_16x16x32_bf16 v[52:55], v[148:151], v[206:209], v[52:55]
	v_mfma_f32_16x16x32_bf16 v[48:51], v[188:191], v[206:209], v[48:51]
	v_mfma_f32_16x16x32_bf16 v[32:35], v[188:191], v[214:217], v[32:35]
	v_mfma_f32_16x16x32_bf16 v[36:39], v[148:151], v[214:217], v[36:39]
	v_mfma_f32_16x16x32_bf16 v[20:23], v[148:151], v[222:225], v[20:23]
	v_mfma_f32_16x16x32_bf16 v[16:19], v[188:191], v[222:225], v[16:19]
	v_mfma_f32_16x16x32_bf16 v[0:3], v[188:191], v[234:237], v[0:3]
	v_mfma_f32_16x16x32_bf16 v[4:7], v[148:151], v[234:237], v[4:7]
	s_setprio 0
	s_barrier
	s_add_i32 s29, 0, 0x18000
	s_add_i32 s38, 0, 0x1c000
	v_add_u32_e32 v140, s29, v169
	v_add_u32_e32 v164, s38, v169
	ds_read_b128 v[128:131], v140
	ds_read_b128 v[132:135], v140 offset:1024
	ds_read_b128 v[136:139], v140 offset:2048
	ds_read_b128 v[140:143], v140 offset:3072
	ds_read_b128 v[144:147], v164
	ds_read_b128 v[148:151], v164 offset:1024
	ds_read_b128 v[184:187], v164 offset:2048
	ds_read_b128 v[188:191], v164 offset:3072
	s_add_u32 s8, s8, 0x40000
	s_addc_u32 s9, s9, 0
	s_mov_b32 m0, s76
	v_lshl_add_u64 v[244:245], s[8:9], 0, v[156:157]
	ds_read_b128 v[202:205], v194 offset:32768
	ds_read_b128 v[206:209], v194 offset:33792
	ds_read_b128 v[210:213], v194 offset:34816
	ds_read_b128 v[214:217], v194 offset:35840
	ds_read_b128 v[218:221], v194 offset:36864
	ds_read_b128 v[222:225], v194 offset:37888
	ds_read_b128 v[230:233], v194 offset:38912
	ds_read_b128 v[234:237], v194 offset:39936
	global_load_lds_dwordx4 v[244:245], off
	v_lshl_add_u64 v[244:245], s[8:9], 0, v[160:161]
	s_mov_b32 m0, s77
	s_nop 0
	global_load_lds_dwordx4 v[244:245], off
	s_waitcnt vmcnt(8)
	s_waitcnt lgkmcnt(0)
	s_barrier
	s_setprio 1
	s_waitcnt lgkmcnt(0)
	v_mfma_f32_16x16x32_bf16 v[124:127], v[128:131], v[202:205], v[124:127]
	v_mfma_f32_16x16x32_bf16 v[120:123], v[136:139], v[202:205], v[120:123]
	v_mfma_f32_16x16x32_bf16 v[104:107], v[136:139], v[210:213], v[104:107]
	v_mfma_f32_16x16x32_bf16 v[108:111], v[128:131], v[210:213], v[108:111]
	v_mfma_f32_16x16x32_bf16 v[92:95], v[128:131], v[218:221], v[92:95]
	v_mfma_f32_16x16x32_bf16 v[88:91], v[136:139], v[218:221], v[88:91]
	v_mfma_f32_16x16x32_bf16 v[72:75], v[136:139], v[230:233], v[72:75]
	v_mfma_f32_16x16x32_bf16 v[76:79], v[128:131], v[230:233], v[76:79]
	v_mfma_f32_16x16x32_bf16 v[124:127], v[132:135], v[206:209], v[124:127]
	v_mfma_f32_16x16x32_bf16 v[120:123], v[140:143], v[206:209], v[120:123]
	v_mfma_f32_16x16x32_bf16 v[104:107], v[140:143], v[214:217], v[104:107]
	v_mfma_f32_16x16x32_bf16 v[108:111], v[132:135], v[214:217], v[108:111]
	v_mfma_f32_16x16x32_bf16 v[92:95], v[132:135], v[222:225], v[92:95]
	v_mfma_f32_16x16x32_bf16 v[88:91], v[140:143], v[222:225], v[88:91]
	v_mfma_f32_16x16x32_bf16 v[72:75], v[140:143], v[234:237], v[72:75]
	v_mfma_f32_16x16x32_bf16 v[76:79], v[132:135], v[234:237], v[76:79]
	s_setprio 0
	s_setprio 1
	v_mfma_f32_16x16x32_bf16 v[116:119], v[144:147], v[202:205], v[116:119]
	v_mfma_f32_16x16x32_bf16 v[112:115], v[184:187], v[202:205], v[112:115]
	v_mfma_f32_16x16x32_bf16 v[96:99], v[184:187], v[210:213], v[96:99]
	v_mfma_f32_16x16x32_bf16 v[100:103], v[144:147], v[210:213], v[100:103]
	v_mfma_f32_16x16x32_bf16 v[84:87], v[144:147], v[218:221], v[84:87]
	v_mfma_f32_16x16x32_bf16 v[80:83], v[184:187], v[218:221], v[80:83]
	v_mfma_f32_16x16x32_bf16 v[64:67], v[184:187], v[230:233], v[64:67]
	v_mfma_f32_16x16x32_bf16 v[68:71], v[144:147], v[230:233], v[68:71]
	v_mfma_f32_16x16x32_bf16 v[116:119], v[148:151], v[206:209], v[116:119]
	v_mfma_f32_16x16x32_bf16 v[112:115], v[188:191], v[206:209], v[112:115]
	v_mfma_f32_16x16x32_bf16 v[96:99], v[188:191], v[214:217], v[96:99]
	v_mfma_f32_16x16x32_bf16 v[100:103], v[148:151], v[214:217], v[100:103]
	v_mfma_f32_16x16x32_bf16 v[84:87], v[148:151], v[222:225], v[84:87]
	v_mfma_f32_16x16x32_bf16 v[80:83], v[188:191], v[222:225], v[80:83]
	v_mfma_f32_16x16x32_bf16 v[64:67], v[188:191], v[234:237], v[64:67]
	v_mfma_f32_16x16x32_bf16 v[68:71], v[148:151], v[234:237], v[68:71]
	s_setprio 0
	s_barrier
; #define PG8_STAGE(bufoff, gbase, voff) do { _Pragma("unroll") for (int _i = 0; _i < 2; ++_i) \
;         __builtin_amdgcn_global_load_lds((const unsigned*)((const char*)(gbase) + (voff)[_i]), (PG8_LAS unsigned*)(lds + (bufoff) + ldsw + _i * 8192), 16, 0, 0); } while (0)
; #define PG8_LDA(dst, b, h) do { _Pragma("unroll") for (int m = 0; m < 4; ++m) _Pragma("unroll") for (int k = 0; k < 2; ++k) dst[m][k] = *(const PG8_LAS bf16x8*)(lds + PG8_SA(b, h) + aoff + m * 2048 + k * 1024); } while (0)
; #define PG8_MMA(ai, bj, At, Bt) do { __builtin_amdgcn_s_setprio(1); _Pragma("unroll") for (int m = 0; m < 4; ++m) _Pragma("unroll") for (int n = 0; n < 2; ++n) _Pragma("unroll") for (int k = 0; k < 2; ++k) \
;         acc[ai][bj][m][n] = __builtin_amdgcn_mfma_f32_16x16x32_bf16(Bt[n][k], At[m][k], acc[ai][bj][m][n], 0, 0, 0); __builtin_amdgcn_s_setprio(0); } while (0)
; #define PG8_WAIT_V(n) asm volatile("s_waitcnt vmcnt(" #n ")" ::: "memory")
; #define PG8_WAIT_L(n) asm volatile("s_waitcnt lgkmcnt(" #n ")" ::: "memory")
; #define PG8_BAR __builtin_amdgcn_s_barrier()
; #define PG8_SCHED __builtin_amdgcn_sched_barrier(0)
; template <class Epi, class Sched, bool ALIGN_EPI = false, bool SP2 = false>
; __device__ __forceinline__ void gemm_phase(PG8_LAS unsigned char* lds, const Gemm g, const Sched& S, const Epi& E) {
;     ...
;             PG8_LDA(At, 1, 1); PG8_STAGE(PG8_SB(1, 0), b3, voffB); PG8_STAGE(PG8_SB(1, 1), b3 + hstep, voffB); PG8_STAGE(PG8_SA(1, 0), a3, voffA);
;             PG8_WAIT_V(8); PG8_WAIT_L(0); PG8_BAR; PG8_MMA(1, 0, At, B0); PG8_MMA(1, 1, At, B1); PG8_BAR; PG8_SCHED;
;     ...
;         if constexpr (ALIGN_EPI) { if (wr == 0) PG8_BAR; }
	s_add_i32 s8, s29, s74
	v_lshl_add_u64 v[192:193], v[192:193], 0, s[22:23]
	s_mov_b32 m0, s8
	ds_read_b128 v[202:205], v194 offset:49152
	ds_read_b128 v[206:209], v194 offset:50176
	ds_read_b128 v[210:213], v194 offset:51200
	ds_read_b128 v[214:217], v194 offset:52224
	ds_read_b128 v[218:221], v194 offset:53248
	ds_read_b128 v[222:225], v194 offset:54272
	ds_read_b128 v[230:233], v194 offset:55296
	ds_read_b128 v[234:237], v194 offset:56320
	global_load_lds_dwordx4 v[192:193], off
	s_add_i32 m0, s8, 0x2000
	s_add_u32 s6, s6, 0x40080
	v_lshl_add_u64 v[192:193], v[238:239], 0, s[22:23]
	s_addc_u32 s7, s7, 0
	s_add_i32 s8, s38, s74
	global_load_lds_dwordx4 v[192:193], off
	v_lshl_add_u64 v[192:193], s[6:7], 0, v[158:159]
	s_mov_b32 m0, s8
	s_nop 0
	global_load_lds_dwordx4 v[192:193], off
	v_lshl_add_u64 v[192:193], s[6:7], 0, v[162:163]
	s_add_i32 m0, s8, 0x2000
	s_nop 0
	global_load_lds_dwordx4 v[192:193], off
	v_lshl_add_u64 v[192:193], v[240:241], 0, s[22:23]
	s_mov_b32 m0, s95
	s_nop 0
	global_load_lds_dwordx4 v[192:193], off
	v_lshl_add_u64 v[192:193], v[242:243], 0, s[22:23]
	s_mov_b32 m0, s96
	s_nop 0
	global_load_lds_dwordx4 v[192:193], off
	s_waitcnt vmcnt(8)
	s_waitcnt lgkmcnt(0)
	s_barrier
	s_setprio 1
	s_waitcnt lgkmcnt(0)
	v_mfma_f32_16x16x32_bf16 v[60:63], v[128:131], v[202:205], v[60:63]
	v_mfma_f32_16x16x32_bf16 v[56:59], v[136:139], v[202:205], v[56:59]
	v_mfma_f32_16x16x32_bf16 v[40:43], v[136:139], v[210:213], v[40:43]
	v_mfma_f32_16x16x32_bf16 v[44:47], v[128:131], v[210:213], v[44:47]
	v_mfma_f32_16x16x32_bf16 v[28:31], v[128:131], v[218:221], v[28:31]
	v_mfma_f32_16x16x32_bf16 v[24:27], v[136:139], v[218:221], v[24:27]
	v_mfma_f32_16x16x32_bf16 v[8:11], v[136:139], v[230:233], v[8:11]
	v_mfma_f32_16x16x32_bf16 v[12:15], v[128:131], v[230:233], v[12:15]
	v_mfma_f32_16x16x32_bf16 v[60:63], v[132:135], v[206:209], v[60:63]
	v_mfma_f32_16x16x32_bf16 v[56:59], v[140:143], v[206:209], v[56:59]
	v_mfma_f32_16x16x32_bf16 v[40:43], v[140:143], v[214:217], v[40:43]
	v_mfma_f32_16x16x32_bf16 v[44:47], v[132:135], v[214:217], v[44:47]
	v_mfma_f32_16x16x32_bf16 v[28:31], v[132:135], v[222:225], v[28:31]
	v_mfma_f32_16x16x32_bf16 v[24:27], v[140:143], v[222:225], v[24:27]
	v_mfma_f32_16x16x32_bf16 v[8:11], v[140:143], v[234:237], v[8:11]
	v_mfma_f32_16x16x32_bf16 v[12:15], v[132:135], v[234:237], v[12:15]
	s_setprio 0
	s_setprio 1
	v_mfma_f32_16x16x32_bf16 v[52:55], v[144:147], v[202:205], v[52:55]
	v_mfma_f32_16x16x32_bf16 v[48:51], v[184:187], v[202:205], v[48:51]
	v_mfma_f32_16x16x32_bf16 v[32:35], v[184:187], v[210:213], v[32:35]
	v_mfma_f32_16x16x32_bf16 v[36:39], v[144:147], v[210:213], v[36:39]
	v_mfma_f32_16x16x32_bf16 v[20:23], v[144:147], v[218:221], v[20:23]
	v_mfma_f32_16x16x32_bf16 v[16:19], v[184:187], v[218:221], v[16:19]
	v_mfma_f32_16x16x32_bf16 v[0:3], v[184:187], v[230:233], v[0:3]
	v_mfma_f32_16x16x32_bf16 v[4:7], v[144:147], v[230:233], v[4:7]
	v_mfma_f32_16x16x32_bf16 v[52:55], v[148:151], v[206:209], v[52:55]
	v_mfma_f32_16x16x32_bf16 v[48:51], v[188:191], v[206:209], v[48:51]
	v_mfma_f32_16x16x32_bf16 v[32:35], v[188:191], v[214:217], v[32:35]
	v_mfma_f32_16x16x32_bf16 v[36:39], v[148:151], v[214:217], v[36:39]
	v_mfma_f32_16x16x32_bf16 v[20:23], v[148:151], v[222:225], v[20:23]
	v_mfma_f32_16x16x32_bf16 v[16:19], v[188:191], v[222:225], v[16:19]
	v_mfma_f32_16x16x32_bf16 v[0:3], v[188:191], v[234:237], v[0:3]
	v_mfma_f32_16x16x32_bf16 v[4:7], v[148:151], v[234:237], v[4:7]
	s_setprio 0
	s_barrier
	s_mov_b32 s99, 0
	s_add_i32 s27, s27, 2
	s_add_u32 s4, s4, 0x100
	s_addc_u32 s5, s5, 0
	s_add_u32 s24, s24, 0x100
	s_addc_u32 s25, s25, 0
	s_cmp_gt_u32 s27, 13
	s_cbranch_scc0 .LBB0_121
	s_and_b64 vcc, exec, s[70:71]
	s_cbranch_vccz .LBB0_124
	s_barrier

; #define PG8_STAGE(bufoff, gbase, voff) do { _Pragma("unroll") for (int _i = 0; _i < 2; ++_i) \
;         __builtin_amdgcn_global_load_lds((const unsigned*)((const char*)(gbase) + (voff)[_i]), (PG8_LAS unsigned*)(lds + (bufoff) + ldsw + _i * 8192), 16, 0, 0); } while (0)
; #define PG8_LDA(dst, b, h) do { _Pragma("unroll") for (int m = 0; m < 4; ++m) _Pragma("unroll") for (int k = 0; k < 2; ++k) dst[m][k] = *(const PG8_LAS bf16x8*)(lds + PG8_SA(b, h) + aoff + m * 2048 + k * 1024); } while (0)
; #define PG8_MMA(ai, bj, At, Bt) do { __builtin_amdgcn_s_setprio(1); _Pragma("unroll") for (int m = 0; m < 4; ++m) _Pragma("unroll") for (int n = 0; n < 2; ++n) _Pragma("unroll") for (int k = 0; k < 2; ++k) \
;         acc[ai][bj][m][n] = __builtin_amdgcn_mfma_f32_16x16x32_bf16(Bt[n][k], At[m][k], acc[ai][bj][m][n], 0, 0, 0); __builtin_amdgcn_s_setprio(0); } while (0)
; #define PG8_WAIT_V(n) asm volatile("s_waitcnt vmcnt(" #n ")" ::: "memory")
; #define PG8_WAIT_L(n) asm volatile("s_waitcnt lgkmcnt(" #n ")" ::: "memory")
; #define PG8_BAR __builtin_amdgcn_s_barrier()
; #define PG8_SCHED __builtin_amdgcn_sched_barrier(0)
; template <class Epi, class Sched, bool ALIGN_EPI = false, bool SP2 = false>
; __device__ __forceinline__ void gemm_phase(PG8_LAS unsigned char* lds, const Gemm g, const Sched& S, const Epi& E) {
;     ...
;             PG8_WAIT_V(8); PG8_WAIT_L(0); PG8_BAR; PG8_MMA(0, 0, At, B0); PG8_MMA(0, 1, At, B1); PG8_BAR; PG8_SCHED;
;             PG8_LDA(At, 0, 1); PG8_STAGE(PG8_SB(0, 0), b2, voffB); PG8_STAGE(PG8_SB(0, 1), b2 + hstep, voffB); PG8_STAGE(PG8_SA(0, 0), a2, voffA);
.Lrj_P3a_0:
	s_waitcnt lgkmcnt(0)
	s_barrier
	s_setprio 1
	s_waitcnt lgkmcnt(0)
	v_mfma_f32_16x16x32_bf16 v[124:127], v[144:147], v[184:187], v[124:127]
	v_mfma_f32_16x16x32_bf16 v[120:123], v[160:163], v[184:187], v[120:123]
	v_mfma_f32_16x16x32_bf16 v[104:107], v[160:163], v[192:195], v[104:107]
	v_mfma_f32_16x16x32_bf16 v[112:115], v[144:147], v[192:195], v[112:115]
	v_mfma_f32_16x16x32_bf16 v[96:99], v[144:147], v[200:203], v[96:99]
	v_mfma_f32_16x16x32_bf16 v[88:91], v[160:163], v[200:203], v[88:91]
	v_mfma_f32_16x16x32_bf16 v[72:75], v[160:163], v[208:211], v[72:75]
	v_mfma_f32_16x16x32_bf16 v[80:83], v[144:147], v[208:211], v[80:83]
	v_mfma_f32_16x16x32_bf16 v[124:127], v[156:159], v[188:191], v[124:127]
	v_mfma_f32_16x16x32_bf16 v[120:123], v[164:167], v[188:191], v[120:123]
	v_mfma_f32_16x16x32_bf16 v[104:107], v[164:167], v[196:199], v[104:107]
	v_mfma_f32_16x16x32_bf16 v[112:115], v[156:159], v[196:199], v[112:115]
	v_mfma_f32_16x16x32_bf16 v[96:99], v[156:159], v[204:207], v[96:99]
	v_mfma_f32_16x16x32_bf16 v[88:91], v[164:167], v[204:207], v[88:91]
	v_mfma_f32_16x16x32_bf16 v[72:75], v[164:167], v[212:215], v[72:75]
	v_mfma_f32_16x16x32_bf16 v[80:83], v[156:159], v[212:215], v[80:83]
	s_setprio 0
	s_setprio 1
	v_mfma_f32_16x16x32_bf16 v[116:119], v[168:171], v[184:187], v[116:119]
	v_mfma_f32_16x16x32_bf16 v[108:111], v[176:179], v[184:187], v[108:111]
	v_mfma_f32_16x16x32_bf16 v[92:95], v[176:179], v[192:195], v[92:95]
	v_mfma_f32_16x16x32_bf16 v[100:103], v[168:171], v[192:195], v[100:103]
	v_mfma_f32_16x16x32_bf16 v[84:87], v[168:171], v[200:203], v[84:87]
	v_mfma_f32_16x16x32_bf16 v[76:79], v[176:179], v[200:203], v[76:79]
	v_mfma_f32_16x16x32_bf16 v[64:67], v[176:179], v[208:211], v[64:67]
	v_mfma_f32_16x16x32_bf16 v[68:71], v[168:171], v[208:211], v[68:71]
	v_mfma_f32_16x16x32_bf16 v[116:119], v[172:175], v[188:191], v[116:119]
	v_mfma_f32_16x16x32_bf16 v[108:111], v[180:183], v[188:191], v[108:111]
	v_mfma_f32_16x16x32_bf16 v[92:95], v[180:183], v[196:199], v[92:95]
	v_mfma_f32_16x16x32_bf16 v[100:103], v[172:175], v[196:199], v[100:103]
	v_mfma_f32_16x16x32_bf16 v[84:87], v[172:175], v[204:207], v[84:87]
	v_mfma_f32_16x16x32_bf16 v[76:79], v[180:183], v[204:207], v[76:79]
	v_mfma_f32_16x16x32_bf16 v[64:67], v[180:183], v[212:215], v[64:67]
	v_mfma_f32_16x16x32_bf16 v[68:71], v[172:175], v[212:215], v[68:71]
	s_setprio 0
	s_barrier
	s_add_i32 s75, s67, s43
	v_lshl_add_u64 v[148:149], s[38:39], 0, v[132:133]
	s_mov_b32 m0, s75
	ds_read_b128 v[184:187], v155 offset:16384
	ds_read_b128 v[188:191], v155 offset:17408
	ds_read_b128 v[192:195], v155 offset:18432
	ds_read_b128 v[196:199], v155 offset:19456
	ds_read_b128 v[200:203], v155 offset:20480
	ds_read_b128 v[204:207], v155 offset:21504
	ds_read_b128 v[208:211], v155 offset:22528
	ds_read_b128 v[212:215], v155 offset:23552
	global_load_lds_dwordx4 v[148:149], off
	s_add_i32 m0, s75, 0x2000
	s_add_u32 s76, s38, 0x20000
	v_lshl_add_u64 v[216:217], s[38:39], 0, v[128:129]
	s_addc_u32 s77, s39, 0
	s_add_i32 s75, s68, s43
	global_load_lds_dwordx4 v[216:217], off
	v_lshl_add_u64 v[218:219], s[76:77], 0, v[132:133]
	s_mov_b32 m0, s75
	v_lshl_add_u64 v[220:221], s[40:41], 0, v[130:131]
	global_load_lds_dwordx4 v[218:219], off
	v_lshl_add_u64 v[218:219], s[76:77], 0, v[128:129]
	s_add_i32 m0, s75, 0x2000
	s_nop 0
	global_load_lds_dwordx4 v[218:219], off
	v_lshl_add_u64 v[218:219], s[40:41], 0, v[134:135]
	s_mov_b32 m0, s35
	s_nop 0
	global_load_lds_dwordx4 v[218:219], off
	s_mov_b32 m0, s52
	s_nop 0
	global_load_lds_dwordx4 v[220:221], off
	s_cmp_eq_u32 s99, 1
	s_cbranch_scc1 .Lrw_P3a_1
	s_waitcnt vmcnt(8)
	s_branch .Lrj_P3a_1

; #define PG8_STAGE(bufoff, gbase, voff) do { _Pragma("unroll") for (int _i = 0; _i < 2; ++_i) \
;         __builtin_amdgcn_global_load_lds((const unsigned*)((const char*)(gbase) + (voff)[_i]), (PG8_LAS unsigned*)(lds + (bufoff) + ldsw + _i * 8192), 16, 0, 0); } while (0)
; #define PG8_LDA(dst, b, h) do { _Pragma("unroll") for (int m = 0; m < 4; ++m) _Pragma("unroll") for (int k = 0; k < 2; ++k) dst[m][k] = *(const PG8_LAS bf16x8*)(lds + PG8_SA(b, h) + aoff + m * 2048 + k * 1024); } while (0)
; #define PG8_LDB(dst, b, h) do { _Pragma("unroll") for (int n = 0; n < 2; ++n) _Pragma("unroll") for (int k = 0; k < 2; ++k) dst[n][k] = *(const PG8_LAS bf16x8*)(lds + PG8_SB(b, h) + boff + n * 2048 + k * 1024); } while (0)
; #define PG8_MMA(ai, bj, At, Bt) do { __builtin_amdgcn_s_setprio(1); _Pragma("unroll") for (int m = 0; m < 4; ++m) _Pragma("unroll") for (int n = 0; n < 2; ++n) _Pragma("unroll") for (int k = 0; k < 2; ++k) \
;         acc[ai][bj][m][n] = __builtin_amdgcn_mfma_f32_16x16x32_bf16(Bt[n][k], At[m][k], acc[ai][bj][m][n], 0, 0, 0); __builtin_amdgcn_s_setprio(0); } while (0)
; #define PG8_WAIT_V(n) asm volatile("s_waitcnt vmcnt(" #n ")" ::: "memory")
; #define PG8_WAIT_L(n) asm volatile("s_waitcnt lgkmcnt(" #n ")" ::: "memory")
; #define PG8_BAR __builtin_amdgcn_s_barrier()
; #define PG8_SCHED __builtin_amdgcn_sched_barrier(0)
; template <class Epi, class Sched, bool ALIGN_EPI = false, bool SP2 = false>
; __device__ __forceinline__ void gemm_phase(PG8_LAS unsigned char* lds, const Gemm g, const Sched& S, const Epi& E) {
;     ...
;             PG8_WAIT_V(8); PG8_WAIT_L(0); PG8_BAR; PG8_MMA(1, 0, At, B0); PG8_MMA(1, 1, At, B1); PG8_BAR; PG8_SCHED;
;             PG8_LDB(B0, 1, 0); PG8_LDB(B1, 1, 1); PG8_SCHED; PG8_LDA(At, 1, 0); PG8_STAGE(PG8_SA(0, 1), a2 + hstep, voffA);
;             PG8_WAIT_V(8); PG8_WAIT_L(0); PG8_BAR; PG8_MMA(0, 0, At, B0); PG8_MMA(0, 1, At, B1); PG8_BAR; PG8_SCHED;
.Lrj_P3a_1:
	s_waitcnt lgkmcnt(0)
	s_barrier
	s_setprio 1
	s_waitcnt lgkmcnt(0)
	v_mfma_f32_16x16x32_bf16 v[60:63], v[144:147], v[184:187], v[60:63]
	v_mfma_f32_16x16x32_bf16 v[56:59], v[160:163], v[184:187], v[56:59]
	v_mfma_f32_16x16x32_bf16 v[40:43], v[160:163], v[192:195], v[40:43]
	v_mfma_f32_16x16x32_bf16 v[48:51], v[144:147], v[192:195], v[48:51]
	v_mfma_f32_16x16x32_bf16 v[32:35], v[144:147], v[200:203], v[32:35]
	v_mfma_f32_16x16x32_bf16 v[24:27], v[160:163], v[200:203], v[24:27]
	v_mfma_f32_16x16x32_bf16 v[8:11], v[160:163], v[208:211], v[8:11]
	v_mfma_f32_16x16x32_bf16 v[16:19], v[144:147], v[208:211], v[16:19]
	v_mfma_f32_16x16x32_bf16 v[60:63], v[156:159], v[188:191], v[60:63]
	v_mfma_f32_16x16x32_bf16 v[56:59], v[164:167], v[188:191], v[56:59]
	v_mfma_f32_16x16x32_bf16 v[40:43], v[164:167], v[196:199], v[40:43]
	v_mfma_f32_16x16x32_bf16 v[48:51], v[156:159], v[196:199], v[48:51]
	v_mfma_f32_16x16x32_bf16 v[32:35], v[156:159], v[204:207], v[32:35]
	v_mfma_f32_16x16x32_bf16 v[24:27], v[164:167], v[204:207], v[24:27]
	v_mfma_f32_16x16x32_bf16 v[8:11], v[164:167], v[212:215], v[8:11]
	v_mfma_f32_16x16x32_bf16 v[16:19], v[156:159], v[212:215], v[16:19]
	s_setprio 0
	s_setprio 1
	v_mfma_f32_16x16x32_bf16 v[52:55], v[168:171], v[184:187], v[52:55]
	v_mfma_f32_16x16x32_bf16 v[44:47], v[176:179], v[184:187], v[44:47]
	v_mfma_f32_16x16x32_bf16 v[28:31], v[176:179], v[192:195], v[28:31]
	v_mfma_f32_16x16x32_bf16 v[36:39], v[168:171], v[192:195], v[36:39]
	v_mfma_f32_16x16x32_bf16 v[20:23], v[168:171], v[200:203], v[20:23]
	v_mfma_f32_16x16x32_bf16 v[12:15], v[176:179], v[200:203], v[12:15]
	v_mfma_f32_16x16x32_bf16 v[0:3], v[176:179], v[208:211], v[0:3]
	v_mfma_f32_16x16x32_bf16 v[4:7], v[168:171], v[208:211], v[4:7]
	v_mfma_f32_16x16x32_bf16 v[52:55], v[172:175], v[188:191], v[52:55]
	v_mfma_f32_16x16x32_bf16 v[44:47], v[180:183], v[188:191], v[44:47]
	v_mfma_f32_16x16x32_bf16 v[28:31], v[180:183], v[196:199], v[28:31]
	v_mfma_f32_16x16x32_bf16 v[36:39], v[172:175], v[196:199], v[36:39]
	v_mfma_f32_16x16x32_bf16 v[20:23], v[172:175], v[204:207], v[20:23]
	v_mfma_f32_16x16x32_bf16 v[12:15], v[180:183], v[204:207], v[12:15]
	v_mfma_f32_16x16x32_bf16 v[0:3], v[180:183], v[212:215], v[0:3]
	v_mfma_f32_16x16x32_bf16 v[4:7], v[172:175], v[212:215], v[4:7]
	s_setprio 0
	s_barrier
	s_add_i32 s75, 0, 0x18000
	s_add_i32 s76, 0, 0x1c000
	v_add_u32_e32 v164, s75, v151
	v_add_u32_e32 v180, s76, v151
	ds_read_b128 v[144:147], v164
	ds_read_b128 v[156:159], v164 offset:1024
	ds_read_b128 v[160:163], v164 offset:2048
	ds_read_b128 v[164:167], v164 offset:3072
	ds_read_b128 v[168:171], v180
	ds_read_b128 v[172:175], v180 offset:1024
	ds_read_b128 v[176:179], v180 offset:2048
	ds_read_b128 v[180:183], v180 offset:3072
	s_add_u32 s40, s40, 0x20000
	s_addc_u32 s41, s41, 0
	s_mov_b32 m0, s53
	v_lshl_add_u64 v[222:223], s[40:41], 0, v[134:135]
	ds_read_b128 v[184:187], v155 offset:32768
	ds_read_b128 v[188:191], v155 offset:33792
	ds_read_b128 v[192:195], v155 offset:34816
	ds_read_b128 v[196:199], v155 offset:35840
	ds_read_b128 v[200:203], v155 offset:36864
	ds_read_b128 v[204:207], v155 offset:37888
	ds_read_b128 v[208:211], v155 offset:38912
	ds_read_b128 v[212:215], v155 offset:39936
	global_load_lds_dwordx4 v[222:223], off
	v_lshl_add_u64 v[222:223], s[40:41], 0, v[130:131]
	s_mov_b32 m0, s60
	s_nop 0
	global_load_lds_dwordx4 v[222:223], off
	s_waitcnt vmcnt(8)
	s_waitcnt lgkmcnt(0)
	s_barrier
	s_setprio 1
	s_waitcnt lgkmcnt(0)
	v_mfma_f32_16x16x32_bf16 v[124:127], v[144:147], v[184:187], v[124:127]
	v_mfma_f32_16x16x32_bf16 v[120:123], v[160:163], v[184:187], v[120:123]
	v_mfma_f32_16x16x32_bf16 v[104:107], v[160:163], v[192:195], v[104:107]
	v_mfma_f32_16x16x32_bf16 v[112:115], v[144:147], v[192:195], v[112:115]
	v_mfma_f32_16x16x32_bf16 v[96:99], v[144:147], v[200:203], v[96:99]
	v_mfma_f32_16x16x32_bf16 v[88:91], v[160:163], v[200:203], v[88:91]
	v_mfma_f32_16x16x32_bf16 v[72:75], v[160:163], v[208:211], v[72:75]
	v_mfma_f32_16x16x32_bf16 v[80:83], v[144:147], v[208:211], v[80:83]
	v_mfma_f32_16x16x32_bf16 v[124:127], v[156:159], v[188:191], v[124:127]
	v_mfma_f32_16x16x32_bf16 v[120:123], v[164:167], v[188:191], v[120:123]
	v_mfma_f32_16x16x32_bf16 v[104:107], v[164:167], v[196:199], v[104:107]
	v_mfma_f32_16x16x32_bf16 v[112:115], v[156:159], v[196:199], v[112:115]
	v_mfma_f32_16x16x32_bf16 v[96:99], v[156:159], v[204:207], v[96:99]
	v_mfma_f32_16x16x32_bf16 v[88:91], v[164:167], v[204:207], v[88:91]
	v_mfma_f32_16x16x32_bf16 v[72:75], v[164:167], v[212:215], v[72:75]
	v_mfma_f32_16x16x32_bf16 v[80:83], v[156:159], v[212:215], v[80:83]
	s_setprio 0
	s_setprio 1
	v_mfma_f32_16x16x32_bf16 v[116:119], v[168:171], v[184:187], v[116:119]
	v_mfma_f32_16x16x32_bf16 v[108:111], v[176:179], v[184:187], v[108:111]
	v_mfma_f32_16x16x32_bf16 v[92:95], v[176:179], v[192:195], v[92:95]
	v_mfma_f32_16x16x32_bf16 v[100:103], v[168:171], v[192:195], v[100:103]
	v_mfma_f32_16x16x32_bf16 v[84:87], v[168:171], v[200:203], v[84:87]
	v_mfma_f32_16x16x32_bf16 v[76:79], v[176:179], v[200:203], v[76:79]
	v_mfma_f32_16x16x32_bf16 v[64:67], v[176:179], v[208:211], v[64:67]
	v_mfma_f32_16x16x32_bf16 v[68:71], v[168:171], v[208:211], v[68:71]
	v_mfma_f32_16x16x32_bf16 v[116:119], v[172:175], v[188:191], v[116:119]
	v_mfma_f32_16x16x32_bf16 v[108:111], v[180:183], v[188:191], v[108:111]
	v_mfma_f32_16x16x32_bf16 v[92:95], v[180:183], v[196:199], v[92:95]
	v_mfma_f32_16x16x32_bf16 v[100:103], v[172:175], v[196:199], v[100:103]
	v_mfma_f32_16x16x32_bf16 v[84:87], v[172:175], v[204:207], v[84:87]
	v_mfma_f32_16x16x32_bf16 v[76:79], v[180:183], v[204:207], v[76:79]
	v_mfma_f32_16x16x32_bf16 v[64:67], v[180:183], v[212:215], v[64:67]
	v_mfma_f32_16x16x32_bf16 v[68:71], v[172:175], v[212:215], v[68:71]
	s_setprio 0
	s_barrier
; #define PG8_STAGE(bufoff, gbase, voff) do { _Pragma("unroll") for (int _i = 0; _i < 2; ++_i) \
;         __builtin_amdgcn_global_load_lds((const unsigned*)((const char*)(gbase) + (voff)[_i]), (PG8_LAS unsigned*)(lds + (bufoff) + ldsw + _i * 8192), 16, 0, 0); } while (0)
; #define PG8_LDA(dst, b, h) do { _Pragma("unroll") for (int m = 0; m < 4; ++m) _Pragma("unroll") for (int k = 0; k < 2; ++k) dst[m][k] = *(const PG8_LAS bf16x8*)(lds + PG8_SA(b, h) + aoff + m * 2048 + k * 1024); } while (0)
; #define PG8_MMA(ai, bj, At, Bt) do { __builtin_amdgcn_s_setprio(1); _Pragma("unroll") for (int m = 0; m < 4; ++m) _Pragma("unroll") for (int n = 0; n < 2; ++n) _Pragma("unroll") for (int k = 0; k < 2; ++k) \
;         acc[ai][bj][m][n] = __builtin_amdgcn_mfma_f32_16x16x32_bf16(Bt[n][k], At[m][k], acc[ai][bj][m][n], 0, 0, 0); __builtin_amdgcn_s_setprio(0); } while (0)
; #define PG8_WAIT_V(n) asm volatile("s_waitcnt vmcnt(" #n ")" ::: "memory")
; #define PG8_WAIT_L(n) asm volatile("s_waitcnt lgkmcnt(" #n ")" ::: "memory")
; #define PG8_BAR __builtin_amdgcn_s_barrier()
; #define PG8_SCHED __builtin_amdgcn_sched_barrier(0)
; template <class Epi, class Sched, bool ALIGN_EPI = false, bool SP2 = false>
; __device__ __forceinline__ void gemm_phase(PG8_LAS unsigned char* lds, const Gemm g, const Sched& S, const Epi& E) {
;     ...
;             PG8_LDA(At, 1, 1); PG8_STAGE(PG8_SB(1, 0), b3, voffB); PG8_STAGE(PG8_SB(1, 1), b3 + hstep, voffB); PG8_STAGE(PG8_SA(1, 0), a3, voffA);
;             PG8_WAIT_V(8); PG8_WAIT_L(0); PG8_BAR; PG8_MMA(1, 0, At, B0); PG8_MMA(1, 1, At, B1); PG8_BAR; PG8_SCHED;
;     ...
;         if constexpr (ALIGN_EPI) { if (wr == 0) PG8_BAR; }
	s_add_i32 s40, s75, s43
	v_lshl_add_u64 v[148:149], v[148:149], 0, s[12:13]
	s_mov_b32 m0, s40
	ds_read_b128 v[184:187], v155 offset:49152
	ds_read_b128 v[188:191], v155 offset:50176
	ds_read_b128 v[192:195], v155 offset:51200
	ds_read_b128 v[196:199], v155 offset:52224
	ds_read_b128 v[200:203], v155 offset:53248
	ds_read_b128 v[204:207], v155 offset:54272
	ds_read_b128 v[208:211], v155 offset:55296
	ds_read_b128 v[212:215], v155 offset:56320
	global_load_lds_dwordx4 v[148:149], off
	s_add_i32 m0, s40, 0x2000
	s_add_u32 s38, s38, 0x20080
	v_lshl_add_u64 v[148:149], v[216:217], 0, s[12:13]
	s_addc_u32 s39, s39, 0
	s_add_i32 s40, s76, s43
	global_load_lds_dwordx4 v[148:149], off
	v_lshl_add_u64 v[148:149], s[38:39], 0, v[132:133]
	s_mov_b32 m0, s40
	s_nop 0
	global_load_lds_dwordx4 v[148:149], off
	v_lshl_add_u64 v[148:149], s[38:39], 0, v[128:129]
	s_add_i32 m0, s40, 0x2000
	s_nop 0
	global_load_lds_dwordx4 v[148:149], off
	v_lshl_add_u64 v[148:149], v[218:219], 0, s[12:13]
	s_mov_b32 m0, s64
	s_nop 0
	global_load_lds_dwordx4 v[148:149], off
	v_lshl_add_u64 v[148:149], v[220:221], 0, s[12:13]
	s_mov_b32 m0, s65
	s_nop 0
	global_load_lds_dwordx4 v[148:149], off
	s_waitcnt vmcnt(8)
	s_waitcnt lgkmcnt(0)
	s_barrier
	s_setprio 1
	s_waitcnt lgkmcnt(0)
	v_mfma_f32_16x16x32_bf16 v[60:63], v[144:147], v[184:187], v[60:63]
	v_mfma_f32_16x16x32_bf16 v[56:59], v[160:163], v[184:187], v[56:59]
	v_mfma_f32_16x16x32_bf16 v[40:43], v[160:163], v[192:195], v[40:43]
	v_mfma_f32_16x16x32_bf16 v[48:51], v[144:147], v[192:195], v[48:51]
	v_mfma_f32_16x16x32_bf16 v[32:35], v[144:147], v[200:203], v[32:35]
	v_mfma_f32_16x16x32_bf16 v[24:27], v[160:163], v[200:203], v[24:27]
	v_mfma_f32_16x16x32_bf16 v[8:11], v[160:163], v[208:211], v[8:11]
	v_mfma_f32_16x16x32_bf16 v[16:19], v[144:147], v[208:211], v[16:19]
	v_mfma_f32_16x16x32_bf16 v[60:63], v[156:159], v[188:191], v[60:63]
	v_mfma_f32_16x16x32_bf16 v[56:59], v[164:167], v[188:191], v[56:59]
	v_mfma_f32_16x16x32_bf16 v[40:43], v[164:167], v[196:199], v[40:43]
	v_mfma_f32_16x16x32_bf16 v[48:51], v[156:159], v[196:199], v[48:51]
	v_mfma_f32_16x16x32_bf16 v[32:35], v[156:159], v[204:207], v[32:35]
	v_mfma_f32_16x16x32_bf16 v[24:27], v[164:167], v[204:207], v[24:27]
	v_mfma_f32_16x16x32_bf16 v[8:11], v[164:167], v[212:215], v[8:11]
	v_mfma_f32_16x16x32_bf16 v[16:19], v[156:159], v[212:215], v[16:19]
	s_setprio 0
	s_setprio 1
	v_mfma_f32_16x16x32_bf16 v[52:55], v[168:171], v[184:187], v[52:55]
	v_mfma_f32_16x16x32_bf16 v[44:47], v[176:179], v[184:187], v[44:47]
	v_mfma_f32_16x16x32_bf16 v[28:31], v[176:179], v[192:195], v[28:31]
	v_mfma_f32_16x16x32_bf16 v[36:39], v[168:171], v[192:195], v[36:39]
	v_mfma_f32_16x16x32_bf16 v[20:23], v[168:171], v[200:203], v[20:23]
	v_mfma_f32_16x16x32_bf16 v[12:15], v[176:179], v[200:203], v[12:15]
	v_mfma_f32_16x16x32_bf16 v[0:3], v[176:179], v[208:211], v[0:3]
	v_mfma_f32_16x16x32_bf16 v[4:7], v[168:171], v[208:211], v[4:7]
	v_mfma_f32_16x16x32_bf16 v[52:55], v[172:175], v[188:191], v[52:55]
	v_mfma_f32_16x16x32_bf16 v[44:47], v[180:183], v[188:191], v[44:47]
	v_mfma_f32_16x16x32_bf16 v[28:31], v[180:183], v[196:199], v[28:31]
	v_mfma_f32_16x16x32_bf16 v[36:39], v[172:175], v[196:199], v[36:39]
	v_mfma_f32_16x16x32_bf16 v[20:23], v[172:175], v[204:207], v[20:23]
	v_mfma_f32_16x16x32_bf16 v[12:15], v[180:183], v[204:207], v[12:15]
	v_mfma_f32_16x16x32_bf16 v[0:3], v[180:183], v[212:215], v[0:3]
	v_mfma_f32_16x16x32_bf16 v[4:7], v[172:175], v[212:215], v[4:7]
	s_setprio 0
	s_barrier
	s_mov_b32 s99, 0
	s_add_i32 s74, s74, 2
	s_add_u32 s36, s36, 0x100
	s_addc_u32 s37, s37, 0
	s_add_u32 s72, s72, 0x100
	s_addc_u32 s73, s73, 0
	s_cmp_gt_u32 s74, 5
	s_cbranch_scc0 .LBB0_1284
	s_and_b64 vcc, exec, s[14:15]
	s_cbranch_vccz .LBB0_1287
	s_barrier

; #define PG8_STAGE(bufoff, gbase, voff) do { _Pragma("unroll") for (int _i = 0; _i < 2; ++_i) \
;         __builtin_amdgcn_global_load_lds((const unsigned*)((const char*)(gbase) + (voff)[_i]), (PG8_LAS unsigned*)(lds + (bufoff) + ldsw + _i * 8192), 16, 0, 0); } while (0)
; #define PG8_LDA(dst, b, h) do { _Pragma("unroll") for (int m = 0; m < 4; ++m) _Pragma("unroll") for (int k = 0; k < 2; ++k) dst[m][k] = *(const PG8_LAS bf16x8*)(lds + PG8_SA(b, h) + aoff + m * 2048 + k * 1024); } while (0)
; #define PG8_LDB(dst, b, h) do { _Pragma("unroll") for (int n = 0; n < 2; ++n) _Pragma("unroll") for (int k = 0; k < 2; ++k) dst[n][k] = *(const PG8_LAS bf16x8*)(lds + PG8_SB(b, h) + boff + n * 2048 + k * 1024); } while (0)
; #define PG8_MMA(ai, bj, At, Bt) do { __builtin_amdgcn_s_setprio(1); _Pragma("unroll") for (int m = 0; m < 4; ++m) _Pragma("unroll") for (int n = 0; n < 2; ++n) _Pragma("unroll") for (int k = 0; k < 2; ++k) \
;         acc[ai][bj][m][n] = __builtin_amdgcn_mfma_f32_16x16x32_bf16(Bt[n][k], At[m][k], acc[ai][bj][m][n], 0, 0, 0); __builtin_amdgcn_s_setprio(0); } while (0)
; #define PG8_WAIT_V(n) asm volatile("s_waitcnt vmcnt(" #n ")" ::: "memory")
; #define PG8_WAIT_L(n) asm volatile("s_waitcnt lgkmcnt(" #n ")" ::: "memory")
; #define PG8_BAR __builtin_amdgcn_s_barrier()
; #define PG8_SCHED __builtin_amdgcn_sched_barrier(0)
; template <class Epi, class Sched, bool ALIGN_EPI = false, bool SP2 = false>
; __device__ __forceinline__ void gemm_phase(PG8_LAS unsigned char* lds, const Gemm g, const Sched& S, const Epi& E) {
;     ...
;             PG8_WAIT_V(8); PG8_WAIT_L(0); PG8_BAR; PG8_MMA(1, 0, At, B0); PG8_MMA(1, 1, At, B1); PG8_BAR; PG8_SCHED;
;             PG8_LDB(B0, 1, 0); PG8_LDB(B1, 1, 1); PG8_SCHED; PG8_LDA(At, 1, 0); PG8_STAGE(PG8_SA(0, 1), a2 + hstep, voffA);
;             PG8_WAIT_V(8); PG8_WAIT_L(0); PG8_BAR; PG8_MMA(0, 0, At, B0); PG8_MMA(0, 1, At, B1); PG8_BAR; PG8_SCHED;
.Lrj_P3b_1:
	s_mov_b32 s99, 0
	s_waitcnt lgkmcnt(0)
	s_barrier
	s_setprio 1
	s_waitcnt lgkmcnt(0)
	v_mfma_f32_16x16x32_bf16 v[140:143], v[0:3], v[60:63], 0
	v_mfma_f32_16x16x32_bf16 v[158:161], v[0:3], v[104:107], 0
	v_mfma_f32_16x16x32_bf16 v[166:169], v[0:3], v[112:115], 0
	v_mfma_f32_16x16x32_bf16 v[0:3], v[0:3], v[120:123], 0
	v_mfma_f32_16x16x32_bf16 v[140:143], v[4:7], v[100:103], v[140:143]
	v_mfma_f32_16x16x32_bf16 v[158:161], v[4:7], v[108:111], v[158:161]
	v_mfma_f32_16x16x32_bf16 v[166:169], v[4:7], v[116:119], v[166:169]
	v_mfma_f32_16x16x32_bf16 v[0:3], v[4:7], v[124:127], v[0:3]
	v_mfma_f32_16x16x32_bf16 v[4:7], v[8:11], v[120:123], 0
	v_mfma_f32_16x16x32_bf16 v[154:157], v[8:11], v[60:63], 0
	v_mfma_f32_16x16x32_bf16 v[162:165], v[8:11], v[104:107], 0
	v_mfma_f32_16x16x32_bf16 v[170:173], v[8:11], v[112:115], 0
	v_mfma_f32_16x16x32_bf16 v[4:7], v[12:15], v[124:127], v[4:7]
	v_mfma_f32_16x16x32_bf16 v[154:157], v[12:15], v[100:103], v[154:157]
	v_mfma_f32_16x16x32_bf16 v[162:165], v[12:15], v[108:111], v[162:165]
	v_mfma_f32_16x16x32_bf16 v[170:173], v[12:15], v[116:119], v[170:173]
	s_setprio 0
	s_setprio 1
	v_mfma_f32_16x16x32_bf16 v[8:11], v[16:19], v[60:63], 0
	v_mfma_f32_16x16x32_bf16 v[12:15], v[24:27], v[60:63], 0
	v_mfma_f32_16x16x32_bf16 v[8:11], v[20:23], v[100:103], v[8:11]
	v_mfma_f32_16x16x32_bf16 v[12:15], v[28:31], v[100:103], v[12:15]
	v_mfma_f32_16x16x32_bf16 v[60:63], v[16:19], v[104:107], 0
	v_mfma_f32_16x16x32_bf16 v[100:103], v[24:27], v[104:107], 0
	v_mfma_f32_16x16x32_bf16 v[104:107], v[16:19], v[112:115], 0
	v_mfma_f32_16x16x32_bf16 v[16:19], v[16:19], v[120:123], 0
	v_mfma_f32_16x16x32_bf16 v[60:63], v[20:23], v[108:111], v[60:63]
	v_mfma_f32_16x16x32_bf16 v[100:103], v[28:31], v[108:111], v[100:103]
	v_mfma_f32_16x16x32_bf16 v[104:107], v[20:23], v[116:119], v[104:107]
	v_mfma_f32_16x16x32_bf16 v[108:111], v[24:27], v[112:115], 0
	v_mfma_f32_16x16x32_bf16 v[16:19], v[20:23], v[124:127], v[16:19]
	v_mfma_f32_16x16x32_bf16 v[20:23], v[24:27], v[120:123], 0
	v_mfma_f32_16x16x32_bf16 v[108:111], v[28:31], v[116:119], v[108:111]
	v_mfma_f32_16x16x32_bf16 v[20:23], v[28:31], v[124:127], v[20:23]
	s_setprio 0
	s_barrier
	s_add_i32 s37, 0, 0x1c000
	v_add_u32_e32 v153, s37, v147
	ds_read_b128 v[24:27], v152
	ds_read_b128 v[28:31], v152 offset:1024
	ds_read_b128 v[112:115], v152 offset:2048
	ds_read_b128 v[116:119], v152 offset:3072
	ds_read_b128 v[120:123], v153
	ds_read_b128 v[124:127], v153 offset:1024
	ds_read_b128 v[174:177], v153 offset:2048
	ds_read_b128 v[178:181], v153 offset:3072
	s_add_u32 s88, s52, 0x10100
	s_addc_u32 s89, s53, 0
	s_mov_b32 m0, s68
	v_lshl_add_u64 v[220:221], s[88:89], 0, v[134:135]
	ds_read_b128 v[182:185], v151 offset:32768
	ds_read_b128 v[186:189], v151 offset:33792
	ds_read_b128 v[190:193], v151 offset:34816
	ds_read_b128 v[194:197], v151 offset:35840
	ds_read_b128 v[198:201], v151 offset:36864
	ds_read_b128 v[202:205], v151 offset:37888
	ds_read_b128 v[206:209], v151 offset:38912
	ds_read_b128 v[210:213], v151 offset:39936
	global_load_lds_dwordx4 v[220:221], off
	v_lshl_add_u64 v[220:221], s[88:89], 0, v[130:131]
	s_mov_b32 m0, s69
	s_nop 0
	global_load_lds_dwordx4 v[220:221], off
	s_waitcnt vmcnt(8)
	s_waitcnt lgkmcnt(0)
	s_barrier
	s_setprio 1
	s_waitcnt lgkmcnt(0)
	v_mfma_f32_16x16x32_bf16 v[64:67], v[24:27], v[182:185], v[64:67]
	v_mfma_f32_16x16x32_bf16 v[68:71], v[112:115], v[182:185], v[68:71]
	v_mfma_f32_16x16x32_bf16 v[76:79], v[112:115], v[190:193], v[76:79]
	v_mfma_f32_16x16x32_bf16 v[72:75], v[24:27], v[190:193], v[72:75]
	v_mfma_f32_16x16x32_bf16 v[80:83], v[24:27], v[198:201], v[80:83]
	v_mfma_f32_16x16x32_bf16 v[84:87], v[112:115], v[198:201], v[84:87]
	v_mfma_f32_16x16x32_bf16 v[92:95], v[112:115], v[206:209], v[92:95]
	v_mfma_f32_16x16x32_bf16 v[88:91], v[24:27], v[206:209], v[88:91]
	v_mfma_f32_16x16x32_bf16 v[64:67], v[28:31], v[186:189], v[64:67]
	v_mfma_f32_16x16x32_bf16 v[68:71], v[116:119], v[186:189], v[68:71]
	v_mfma_f32_16x16x32_bf16 v[76:79], v[116:119], v[194:197], v[76:79]
	v_mfma_f32_16x16x32_bf16 v[72:75], v[28:31], v[194:197], v[72:75]
	v_mfma_f32_16x16x32_bf16 v[80:83], v[28:31], v[202:205], v[80:83]
	v_mfma_f32_16x16x32_bf16 v[84:87], v[116:119], v[202:205], v[84:87]
	v_mfma_f32_16x16x32_bf16 v[92:95], v[116:119], v[210:213], v[92:95]
	v_mfma_f32_16x16x32_bf16 v[88:91], v[28:31], v[210:213], v[88:91]
	s_setprio 0
	s_setprio 1
	v_mfma_f32_16x16x32_bf16 v[96:99], v[120:123], v[182:185], v[96:99]
	v_mfma_f32_16x16x32_bf16 v[32:35], v[174:177], v[182:185], v[32:35]
	v_mfma_f32_16x16x32_bf16 v[40:43], v[174:177], v[190:193], v[40:43]
	v_mfma_f32_16x16x32_bf16 v[36:39], v[120:123], v[190:193], v[36:39]
	v_mfma_f32_16x16x32_bf16 v[44:47], v[120:123], v[198:201], v[44:47]
	v_mfma_f32_16x16x32_bf16 v[48:51], v[174:177], v[198:201], v[48:51]
	v_mfma_f32_16x16x32_bf16 v[56:59], v[174:177], v[206:209], v[56:59]
	v_mfma_f32_16x16x32_bf16 v[52:55], v[120:123], v[206:209], v[52:55]
	v_mfma_f32_16x16x32_bf16 v[96:99], v[124:127], v[186:189], v[96:99]
	v_mfma_f32_16x16x32_bf16 v[32:35], v[178:181], v[186:189], v[32:35]
	v_mfma_f32_16x16x32_bf16 v[40:43], v[178:181], v[194:197], v[40:43]
	v_mfma_f32_16x16x32_bf16 v[36:39], v[124:127], v[194:197], v[36:39]
	v_mfma_f32_16x16x32_bf16 v[44:47], v[124:127], v[202:205], v[44:47]
	v_mfma_f32_16x16x32_bf16 v[48:51], v[178:181], v[202:205], v[48:51]
	v_mfma_f32_16x16x32_bf16 v[56:59], v[178:181], v[210:213], v[56:59]
	v_mfma_f32_16x16x32_bf16 v[52:55], v[124:127], v[210:213], v[52:55]
	s_setprio 0
	s_barrier
; #define PG8_STAGE(bufoff, gbase, voff) do { _Pragma("unroll") for (int _i = 0; _i < 2; ++_i) \
;         __builtin_amdgcn_global_load_lds((const unsigned*)((const char*)(gbase) + (voff)[_i]), (PG8_LAS unsigned*)(lds + (bufoff) + ldsw + _i * 8192), 16, 0, 0); } while (0)
; #define PG8_LDA(dst, b, h) do { _Pragma("unroll") for (int m = 0; m < 4; ++m) _Pragma("unroll") for (int k = 0; k < 2; ++k) dst[m][k] = *(const PG8_LAS bf16x8*)(lds + PG8_SA(b, h) + aoff + m * 2048 + k * 1024); } while (0)
; #define PG8_LDB(dst, b, h) do { _Pragma("unroll") for (int n = 0; n < 2; ++n) _Pragma("unroll") for (int k = 0; k < 2; ++k) dst[n][k] = *(const PG8_LAS bf16x8*)(lds + PG8_SB(b, h) + boff + n * 2048 + k * 1024); } while (0)
; #define PG8_MMA(ai, bj, At, Bt) do { __builtin_amdgcn_s_setprio(1); _Pragma("unroll") for (int m = 0; m < 4; ++m) _Pragma("unroll") for (int n = 0; n < 2; ++n) _Pragma("unroll") for (int k = 0; k < 2; ++k) \
;         acc[ai][bj][m][n] = __builtin_amdgcn_mfma_f32_16x16x32_bf16(Bt[n][k], At[m][k], acc[ai][bj][m][n], 0, 0, 0); __builtin_amdgcn_s_setprio(0); } while (0)
; #define PG8_WAIT_V(n) asm volatile("s_waitcnt vmcnt(" #n ")" ::: "memory")
; #define PG8_WAIT_L(n) asm volatile("s_waitcnt lgkmcnt(" #n ")" ::: "memory")
; #define PG8_BAR __builtin_amdgcn_s_barrier()
; #define PG8_SCHED __builtin_amdgcn_sched_barrier(0)
; template <class Epi, class Sched, bool ALIGN_EPI = false, bool SP2 = false>
; __device__ __forceinline__ void gemm_phase(PG8_LAS unsigned char* lds, const Gemm g, const Sched& S, const Epi& E) {
;     ...
;             PG8_LDB(B0, 0, 0); PG8_LDB(B1, 0, 1); PG8_SCHED; PG8_LDA(At, 0, 0); PG8_STAGE(PG8_SA(1, 1), a1 + hstep, voffA);
;             PG8_WAIT_V(8); PG8_WAIT_L(0); PG8_BAR; PG8_MMA(0, 0, At, B0); PG8_MMA(0, 1, At, B1); PG8_BAR; PG8_SCHED;
;     ...
;             PG8_LDA(At, 1, 1); PG8_STAGE(PG8_SB(1, 0), b3, voffB); PG8_STAGE(PG8_SB(1, 1), b3 + hstep, voffB); PG8_STAGE(PG8_SA(1, 0), a3, voffA);
;             PG8_WAIT_V(8); PG8_WAIT_L(0); PG8_BAR; PG8_MMA(1, 0, At, B0); PG8_MMA(1, 1, At, B1); PG8_BAR; PG8_SCHED;
	s_add_i32 s83, s81, s47
	s_add_i32 s35, s83, 0x2000
	v_lshl_add_u64 v[144:145], v[144:145], 0, s[22:23]
	s_mov_b32 m0, s83
	s_add_u32 s62, s62, 0x10180
	ds_read_b128 v[182:185], v151 offset:49152
	ds_read_b128 v[186:189], v151 offset:50176
	ds_read_b128 v[190:193], v151 offset:51200
	ds_read_b128 v[194:197], v151 offset:52224
	ds_read_b128 v[198:201], v151 offset:53248
	ds_read_b128 v[202:205], v151 offset:54272
	ds_read_b128 v[206:209], v151 offset:55296
	ds_read_b128 v[210:213], v151 offset:56320
	global_load_lds_dwordx4 v[144:145], off
	v_lshl_add_u64 v[144:145], v[214:215], 0, s[22:23]
	s_mov_b32 m0, s35
	s_addc_u32 s63, s63, 0
	s_add_i32 s37, s37, s47
	global_load_lds_dwordx4 v[144:145], off
	v_lshl_add_u64 v[144:145], s[62:63], 0, v[132:133]
	s_mov_b32 m0, s37
	s_nop 0
	global_load_lds_dwordx4 v[144:145], off
	v_lshl_add_u64 v[144:145], s[62:63], 0, v[128:129]
	s_add_i32 s62, s37, 0x2000
	s_mov_b32 m0, s62
	s_nop 0
	global_load_lds_dwordx4 v[144:145], off
	v_lshl_add_u64 v[144:145], v[216:217], 0, s[22:23]
	s_mov_b32 m0, s70
	s_nop 0
	global_load_lds_dwordx4 v[144:145], off
	v_lshl_add_u64 v[144:145], v[218:219], 0, s[22:23]
	s_mov_b32 m0, s71
	s_nop 0
	global_load_lds_dwordx4 v[144:145], off
	s_waitcnt vmcnt(8)
	s_waitcnt lgkmcnt(0)
	s_barrier
	s_setprio 1
	s_waitcnt lgkmcnt(0)
	v_mfma_f32_16x16x32_bf16 v[0:3], v[24:27], v[206:209], v[0:3]
	v_mfma_f32_16x16x32_bf16 v[4:7], v[112:115], v[206:209], v[4:7]
	v_mfma_f32_16x16x32_bf16 v[154:157], v[112:115], v[182:185], v[154:157]
	v_mfma_f32_16x16x32_bf16 v[140:143], v[24:27], v[182:185], v[140:143]
	v_mfma_f32_16x16x32_bf16 v[158:161], v[24:27], v[190:193], v[158:161]
	v_mfma_f32_16x16x32_bf16 v[162:165], v[112:115], v[190:193], v[162:165]
	v_mfma_f32_16x16x32_bf16 v[170:173], v[112:115], v[198:201], v[170:173]
	v_mfma_f32_16x16x32_bf16 v[166:169], v[24:27], v[198:201], v[166:169]
	v_mfma_f32_16x16x32_bf16 v[0:3], v[28:31], v[210:213], v[0:3]
	v_mfma_f32_16x16x32_bf16 v[4:7], v[116:119], v[210:213], v[4:7]
	v_mfma_f32_16x16x32_bf16 v[154:157], v[116:119], v[186:189], v[154:157]
	v_mfma_f32_16x16x32_bf16 v[140:143], v[28:31], v[186:189], v[140:143]
	v_mfma_f32_16x16x32_bf16 v[158:161], v[28:31], v[194:197], v[158:161]
	v_mfma_f32_16x16x32_bf16 v[162:165], v[116:119], v[194:197], v[162:165]
	v_mfma_f32_16x16x32_bf16 v[170:173], v[116:119], v[202:205], v[170:173]
	v_mfma_f32_16x16x32_bf16 v[166:169], v[28:31], v[202:205], v[166:169]
	s_setprio 0
	s_setprio 1
	v_mfma_f32_16x16x32_bf16 v[8:11], v[120:123], v[182:185], v[8:11]
	v_mfma_f32_16x16x32_bf16 v[12:15], v[174:177], v[182:185], v[12:15]
	v_mfma_f32_16x16x32_bf16 v[24:27], v[120:123], v[190:193], v[60:63]
	v_mfma_f32_16x16x32_bf16 v[28:31], v[174:177], v[190:193], v[100:103]
	v_mfma_f32_16x16x32_bf16 v[60:63], v[120:123], v[198:201], v[104:107]
	v_mfma_f32_16x16x32_bf16 v[100:103], v[174:177], v[198:201], v[108:111]
	v_mfma_f32_16x16x32_bf16 v[16:19], v[120:123], v[206:209], v[16:19]
	v_mfma_f32_16x16x32_bf16 v[20:23], v[174:177], v[206:209], v[20:23]
	v_mfma_f32_16x16x32_bf16 v[8:11], v[124:127], v[186:189], v[8:11]
	v_mfma_f32_16x16x32_bf16 v[12:15], v[178:181], v[186:189], v[12:15]
	v_mfma_f32_16x16x32_bf16 v[24:27], v[124:127], v[194:197], v[24:27]
	v_mfma_f32_16x16x32_bf16 v[28:31], v[178:181], v[194:197], v[28:31]
	v_mfma_f32_16x16x32_bf16 v[60:63], v[124:127], v[202:205], v[60:63]
	v_mfma_f32_16x16x32_bf16 v[100:103], v[178:181], v[202:205], v[100:103]
	v_mfma_f32_16x16x32_bf16 v[16:19], v[124:127], v[210:213], v[16:19]
	v_mfma_f32_16x16x32_bf16 v[20:23], v[178:181], v[210:213], v[20:23]
	s_setprio 0
	s_barrier
	ds_read_b128 v[104:107], v149
	ds_read_b128 v[108:111], v149 offset:1024
	ds_read_b128 v[112:115], v149 offset:2048
	ds_read_b128 v[116:119], v149 offset:3072
	ds_read_b128 v[120:123], v150
	ds_read_b128 v[124:127], v150 offset:1024
	ds_read_b128 v[174:177], v150 offset:2048
	ds_read_b128 v[178:181], v150 offset:3072
	s_add_u32 s52, s52, 0x10180
	s_addc_u32 s53, s53, 0
	s_mov_b32 m0, s73
	v_lshl_add_u64 v[144:145], s[52:53], 0, v[134:135]
	ds_read_b128 v[182:185], v151
	ds_read_b128 v[186:189], v151 offset:1024
	ds_read_b128 v[190:193], v151 offset:2048
	ds_read_b128 v[194:197], v151 offset:3072
	ds_read_b128 v[198:201], v151 offset:4096
	ds_read_b128 v[202:205], v151 offset:5120
	ds_read_b128 v[206:209], v151 offset:6144
	ds_read_b128 v[210:213], v151 offset:7168
	global_load_lds_dwordx4 v[144:145], off
	v_lshl_add_u64 v[144:145], s[52:53], 0, v[130:131]
	s_mov_b32 m0, s74
	s_nop 0
	global_load_lds_dwordx4 v[144:145], off
	s_waitcnt vmcnt(8)
	s_waitcnt lgkmcnt(0)
	s_barrier
; #define PG8_STAGE(bufoff, gbase, voff) do { _Pragma("unroll") for (int _i = 0; _i < 2; ++_i) \
;         __builtin_amdgcn_global_load_lds((const unsigned*)((const char*)(gbase) + (voff)[_i]), (PG8_LAS unsigned*)(lds + (bufoff) + ldsw + _i * 8192), 16, 0, 0); } while (0)
; #define PG8_LDA(dst, b, h) do { _Pragma("unroll") for (int m = 0; m < 4; ++m) _Pragma("unroll") for (int k = 0; k < 2; ++k) dst[m][k] = *(const PG8_LAS bf16x8*)(lds + PG8_SA(b, h) + aoff + m * 2048 + k * 1024); } while (0)
; #define PG8_MMA(ai, bj, At, Bt) do { __builtin_amdgcn_s_setprio(1); _Pragma("unroll") for (int m = 0; m < 4; ++m) _Pragma("unroll") for (int n = 0; n < 2; ++n) _Pragma("unroll") for (int k = 0; k < 2; ++k) \
;         acc[ai][bj][m][n] = __builtin_amdgcn_mfma_f32_16x16x32_bf16(Bt[n][k], At[m][k], acc[ai][bj][m][n], 0, 0, 0); __builtin_amdgcn_s_setprio(0); } while (0)
; #define PG8_WAIT_V(n) asm volatile("s_waitcnt vmcnt(" #n ")" ::: "memory")
; #define PG8_WAIT_L(n) asm volatile("s_waitcnt lgkmcnt(" #n ")" ::: "memory")
; #define PG8_BAR __builtin_amdgcn_s_barrier()
; #define PG8_SCHED __builtin_amdgcn_sched_barrier(0)
; template <class Epi, class Sched, bool ALIGN_EPI = false, bool SP2 = false>
; __device__ __forceinline__ void gemm_phase(PG8_LAS unsigned char* lds, const Gemm g, const Sched& S, const Epi& E) {
;     ...
;             PG8_WAIT_V(8); PG8_WAIT_L(0); PG8_BAR; PG8_MMA(0, 0, At, B0); PG8_MMA(0, 1, At, B1); PG8_BAR; PG8_SCHED;
;             PG8_LDA(At, 0, 1); PG8_STAGE(PG8_SB(0, 0), b2, voffB); PG8_STAGE(PG8_SB(0, 1), b2 + hstep, voffB); PG8_STAGE(PG8_SA(0, 0), a2, voffA);
;             PG8_WAIT_V(8); PG8_WAIT_L(0); PG8_BAR; PG8_MMA(1, 0, At, B0); PG8_MMA(1, 1, At, B1); PG8_BAR; PG8_SCHED;
	s_setprio 1
	s_waitcnt lgkmcnt(0)
	v_mfma_f32_16x16x32_bf16 v[64:67], v[104:107], v[182:185], v[64:67]
	v_mfma_f32_16x16x32_bf16 v[68:71], v[112:115], v[182:185], v[68:71]
	v_mfma_f32_16x16x32_bf16 v[72:75], v[104:107], v[190:193], v[72:75]
	v_mfma_f32_16x16x32_bf16 v[76:79], v[112:115], v[190:193], v[76:79]
	v_mfma_f32_16x16x32_bf16 v[80:83], v[104:107], v[198:201], v[80:83]
	v_mfma_f32_16x16x32_bf16 v[84:87], v[112:115], v[198:201], v[84:87]
	v_mfma_f32_16x16x32_bf16 v[88:91], v[104:107], v[206:209], v[88:91]
	v_mfma_f32_16x16x32_bf16 v[64:67], v[108:111], v[186:189], v[64:67]
	v_mfma_f32_16x16x32_bf16 v[68:71], v[116:119], v[186:189], v[68:71]
	v_mfma_f32_16x16x32_bf16 v[72:75], v[108:111], v[194:197], v[72:75]
	v_mfma_f32_16x16x32_bf16 v[76:79], v[116:119], v[194:197], v[76:79]
	v_mfma_f32_16x16x32_bf16 v[80:83], v[108:111], v[202:205], v[80:83]
	v_mfma_f32_16x16x32_bf16 v[84:87], v[116:119], v[202:205], v[84:87]
	v_mfma_f32_16x16x32_bf16 v[214:217], v[108:111], v[210:213], v[88:91]
	v_mfma_f32_16x16x32_bf16 v[88:91], v[112:115], v[206:209], v[92:95]
	v_mfma_f32_16x16x32_bf16 v[218:221], v[116:119], v[210:213], v[88:91]
	s_setprio 0
	s_setprio 1
	v_mfma_f32_16x16x32_bf16 v[88:91], v[120:123], v[182:185], v[96:99]
	v_mfma_f32_16x16x32_bf16 v[32:35], v[174:177], v[182:185], v[32:35]
	v_mfma_f32_16x16x32_bf16 v[36:39], v[120:123], v[190:193], v[36:39]
	v_mfma_f32_16x16x32_bf16 v[40:43], v[174:177], v[190:193], v[40:43]
	v_mfma_f32_16x16x32_bf16 v[44:47], v[120:123], v[198:201], v[44:47]
	v_mfma_f32_16x16x32_bf16 v[48:51], v[174:177], v[198:201], v[48:51]
	v_mfma_f32_16x16x32_bf16 v[52:55], v[120:123], v[206:209], v[52:55]
	v_mfma_f32_16x16x32_bf16 v[56:59], v[174:177], v[206:209], v[56:59]
	v_mfma_f32_16x16x32_bf16 v[96:99], v[124:127], v[186:189], v[88:91]
	v_mfma_f32_16x16x32_bf16 v[32:35], v[178:181], v[186:189], v[32:35]
	v_mfma_f32_16x16x32_bf16 v[36:39], v[124:127], v[194:197], v[36:39]
	v_mfma_f32_16x16x32_bf16 v[40:43], v[178:181], v[194:197], v[40:43]
	v_mfma_f32_16x16x32_bf16 v[44:47], v[124:127], v[202:205], v[44:47]
	v_mfma_f32_16x16x32_bf16 v[48:51], v[178:181], v[202:205], v[48:51]
	v_mfma_f32_16x16x32_bf16 v[52:55], v[124:127], v[210:213], v[52:55]
	v_mfma_f32_16x16x32_bf16 v[56:59], v[178:181], v[210:213], v[56:59]
	s_setprio 0
	s_barrier
	s_mov_b32 m0, s75
	v_lshl_add_u64 v[144:145], s[64:65], 0, v[132:133]
	s_add_u32 s52, s64, 0x10000
	ds_read_b128 v[88:91], v151 offset:16384
	ds_read_b128 v[92:95], v151 offset:17408
	ds_read_b128 v[182:185], v151 offset:18432
	ds_read_b128 v[186:189], v151 offset:19456
	ds_read_b128 v[190:193], v151 offset:20480
	ds_read_b128 v[194:197], v151 offset:21504
	ds_read_b128 v[198:201], v151 offset:22528
	ds_read_b128 v[202:205], v151 offset:23552
	global_load_lds_dwordx4 v[144:145], off
	v_lshl_add_u64 v[248:249], s[64:65], 0, v[128:129]
	s_mov_b32 m0, s76
	s_addc_u32 s53, s65, 0
	global_load_lds_dwordx4 v[248:249], off
	v_lshl_add_u64 v[206:207], s[52:53], 0, v[132:133]
	s_mov_b32 m0, s77
	v_lshl_add_u64 v[250:251], s[66:67], 0, v[134:135]
	global_load_lds_dwordx4 v[206:207], off
	v_lshl_add_u64 v[206:207], s[52:53], 0, v[128:129]
	s_mov_b32 m0, s80
	v_lshl_add_u64 v[252:253], s[66:67], 0, v[130:131]
	global_load_lds_dwordx4 v[206:207], off
	s_mov_b32 m0, s43
	s_nop 0
	global_load_lds_dwordx4 v[250:251], off
	s_mov_b32 m0, s61
	s_nop 0
	global_load_lds_dwordx4 v[252:253], off
	s_waitcnt vmcnt(8)
	s_waitcnt lgkmcnt(0)
	s_barrier
	s_setprio 1
	s_waitcnt lgkmcnt(0)
	v_mfma_f32_16x16x32_bf16 v[0:3], v[104:107], v[198:201], v[0:3]
	v_mfma_f32_16x16x32_bf16 v[4:7], v[112:115], v[198:201], v[4:7]
	v_mfma_f32_16x16x32_bf16 v[154:157], v[112:115], v[88:91], v[154:157]
	v_mfma_f32_16x16x32_bf16 v[140:143], v[104:107], v[88:91], v[140:143]
	v_mfma_f32_16x16x32_bf16 v[158:161], v[104:107], v[182:185], v[158:161]
	v_mfma_f32_16x16x32_bf16 v[162:165], v[112:115], v[182:185], v[162:165]
	v_mfma_f32_16x16x32_bf16 v[170:173], v[112:115], v[190:193], v[170:173]
	v_mfma_f32_16x16x32_bf16 v[166:169], v[104:107], v[190:193], v[166:169]
	v_mfma_f32_16x16x32_bf16 v[0:3], v[108:111], v[202:205], v[0:3]
	v_mfma_f32_16x16x32_bf16 v[4:7], v[116:119], v[202:205], v[4:7]
	v_mfma_f32_16x16x32_bf16 v[154:157], v[116:119], v[92:95], v[154:157]
	v_mfma_f32_16x16x32_bf16 v[140:143], v[108:111], v[92:95], v[140:143]
	v_mfma_f32_16x16x32_bf16 v[158:161], v[108:111], v[186:189], v[158:161]
	v_mfma_f32_16x16x32_bf16 v[162:165], v[116:119], v[186:189], v[162:165]
	v_mfma_f32_16x16x32_bf16 v[170:173], v[116:119], v[194:197], v[170:173]
	v_mfma_f32_16x16x32_bf16 v[166:169], v[108:111], v[194:197], v[166:169]
	s_setprio 0
	s_setprio 1
	v_mfma_f32_16x16x32_bf16 v[8:11], v[120:123], v[88:91], v[8:11]
	v_mfma_f32_16x16x32_bf16 v[206:209], v[124:127], v[92:95], v[8:11]
	v_mfma_f32_16x16x32_bf16 v[8:11], v[174:177], v[88:91], v[12:15]
	v_mfma_f32_16x16x32_bf16 v[210:213], v[178:181], v[92:95], v[8:11]
	v_mfma_f32_16x16x32_bf16 v[8:11], v[120:123], v[182:185], v[24:27]
	v_mfma_f32_16x16x32_bf16 v[222:225], v[124:127], v[186:189], v[8:11]
	v_mfma_f32_16x16x32_bf16 v[8:11], v[174:177], v[182:185], v[28:31]
	v_mfma_f32_16x16x32_bf16 v[182:185], v[178:181], v[186:189], v[8:11]
	v_mfma_f32_16x16x32_bf16 v[8:11], v[120:123], v[190:193], v[60:63]
	v_mfma_f32_16x16x32_bf16 v[186:189], v[124:127], v[194:197], v[8:11]
	v_mfma_f32_16x16x32_bf16 v[8:11], v[174:177], v[190:193], v[100:103]
	v_mfma_f32_16x16x32_bf16 v[190:193], v[178:181], v[194:197], v[8:11]
	v_mfma_f32_16x16x32_bf16 v[8:11], v[120:123], v[198:201], v[16:19]
	v_mfma_f32_16x16x32_bf16 v[194:197], v[124:127], v[202:205], v[8:11]
	v_mfma_f32_16x16x32_bf16 v[8:11], v[174:177], v[198:201], v[20:23]
	v_mfma_f32_16x16x32_bf16 v[174:177], v[178:181], v[202:205], v[8:11]
	s_setprio 0
	s_barrier
; #define PG8_STAGE(bufoff, gbase, voff) do { _Pragma("unroll") for (int _i = 0; _i < 2; ++_i) \
;         __builtin_amdgcn_global_load_lds((const unsigned*)((const char*)(gbase) + (voff)[_i]), (PG8_LAS unsigned*)(lds + (bufoff) + ldsw + _i * 8192), 16, 0, 0); } while (0)
; #define PG8_LDA(dst, b, h) do { _Pragma("unroll") for (int m = 0; m < 4; ++m) _Pragma("unroll") for (int k = 0; k < 2; ++k) dst[m][k] = *(const PG8_LAS bf16x8*)(lds + PG8_SA(b, h) + aoff + m * 2048 + k * 1024); } while (0)
; #define PG8_LDB(dst, b, h) do { _Pragma("unroll") for (int n = 0; n < 2; ++n) _Pragma("unroll") for (int k = 0; k < 2; ++k) dst[n][k] = *(const PG8_LAS bf16x8*)(lds + PG8_SB(b, h) + boff + n * 2048 + k * 1024); } while (0)
; #define PG8_MMA(ai, bj, At, Bt) do { __builtin_amdgcn_s_setprio(1); _Pragma("unroll") for (int m = 0; m < 4; ++m) _Pragma("unroll") for (int n = 0; n < 2; ++n) _Pragma("unroll") for (int k = 0; k < 2; ++k) \
;         acc[ai][bj][m][n] = __builtin_amdgcn_mfma_f32_16x16x32_bf16(Bt[n][k], At[m][k], acc[ai][bj][m][n], 0, 0, 0); __builtin_amdgcn_s_setprio(0); } while (0)
; #define PG8_WAIT_V(n) asm volatile("s_waitcnt vmcnt(" #n ")" ::: "memory")
; #define PG8_WAIT_L(n) asm volatile("s_waitcnt lgkmcnt(" #n ")" ::: "memory")
; #define PG8_BAR __builtin_amdgcn_s_barrier()
; #define PG8_SCHED __builtin_amdgcn_sched_barrier(0)
; template <class Epi, class Sched, bool ALIGN_EPI = false, bool SP2 = false>
; __device__ __forceinline__ void gemm_phase(PG8_LAS unsigned char* lds, const Gemm g, const Sched& S, const Epi& E) {
;     ...
;             PG8_LDB(B0, 1, 0); PG8_LDB(B1, 1, 1); PG8_SCHED; PG8_LDA(At, 1, 0); PG8_STAGE(PG8_SA(0, 1), a2 + hstep, voffA);
;             PG8_WAIT_V(8); PG8_WAIT_L(0); PG8_BAR; PG8_MMA(0, 0, At, B0); PG8_MMA(0, 1, At, B1); PG8_BAR; PG8_SCHED;
;             PG8_LDA(At, 1, 1); PG8_STAGE(PG8_SB(1, 0), b3, voffB); PG8_STAGE(PG8_SB(1, 1), b3 + hstep, voffB); PG8_STAGE(PG8_SA(1, 0), a3, voffA);
;             PG8_WAIT_V(8); PG8_WAIT_L(0); PG8_BAR; PG8_MMA(1, 0, At, B0); PG8_MMA(1, 1, At, B1); PG8_BAR; PG8_SCHED;
	s_nop 4
	ds_read_b128 v[8:11], v152
	ds_read_b128 v[12:15], v152 offset:1024
	ds_read_b128 v[16:19], v152 offset:2048
	ds_read_b128 v[20:23], v152 offset:3072
	ds_read_b128 v[178:181], v153
	ds_read_b128 v[198:201], v153 offset:1024
	ds_read_b128 v[202:205], v153 offset:2048
	ds_read_b128 v[228:231], v153 offset:3072
	s_add_u32 s52, s66, 0x10000
	s_addc_u32 s53, s67, 0
	s_mov_b32 m0, s68
	v_lshl_add_u64 v[88:89], s[52:53], 0, v[134:135]
	ds_read_b128 v[24:27], v151 offset:32768
	ds_read_b128 v[28:31], v151 offset:33792
	ds_read_b128 v[60:63], v151 offset:34816
	ds_read_b128 v[100:103], v151 offset:35840
	ds_read_b128 v[232:235], v151 offset:36864
	ds_read_b128 v[236:239], v151 offset:37888
	ds_read_b128 v[240:243], v151 offset:38912
	ds_read_b128 v[244:247], v151 offset:39936
	global_load_lds_dwordx4 v[88:89], off
	v_lshl_add_u64 v[88:89], s[52:53], 0, v[130:131]
	s_mov_b32 m0, s69
	s_nop 0
	global_load_lds_dwordx4 v[88:89], off
	s_waitcnt vmcnt(8)
	s_waitcnt lgkmcnt(0)
	s_barrier
	s_setprio 1
	s_waitcnt lgkmcnt(0)
	v_mfma_f32_16x16x32_bf16 v[64:67], v[8:11], v[24:27], v[64:67]
	v_mfma_f32_16x16x32_bf16 v[124:127], v[12:15], v[28:31], v[64:67]
	v_mfma_f32_16x16x32_bf16 v[64:67], v[16:19], v[24:27], v[68:71]
	v_mfma_f32_16x16x32_bf16 v[120:123], v[20:23], v[28:31], v[64:67]
	v_mfma_f32_16x16x32_bf16 v[64:67], v[8:11], v[60:63], v[72:75]
	v_mfma_f32_16x16x32_bf16 v[108:111], v[12:15], v[100:103], v[64:67]
	v_mfma_f32_16x16x32_bf16 v[64:67], v[16:19], v[60:63], v[76:79]
	v_mfma_f32_16x16x32_bf16 v[104:107], v[20:23], v[100:103], v[64:67]
	v_mfma_f32_16x16x32_bf16 v[64:67], v[8:11], v[232:235], v[80:83]
	v_mfma_f32_16x16x32_bf16 v[92:95], v[12:15], v[236:239], v[64:67]
	v_mfma_f32_16x16x32_bf16 v[64:67], v[16:19], v[232:235], v[84:87]
	v_mfma_f32_16x16x32_bf16 v[88:91], v[20:23], v[236:239], v[64:67]
	v_mfma_f32_16x16x32_bf16 v[64:67], v[8:11], v[240:243], v[214:217]
	v_mfma_f32_16x16x32_bf16 v[76:79], v[12:15], v[244:247], v[64:67]
	v_mfma_f32_16x16x32_bf16 v[64:67], v[16:19], v[240:243], v[218:221]
	v_mfma_f32_16x16x32_bf16 v[72:75], v[20:23], v[244:247], v[64:67]
	s_setprio 0
	s_setprio 1
	v_mfma_f32_16x16x32_bf16 v[64:67], v[178:181], v[24:27], v[96:99]
	v_mfma_f32_16x16x32_bf16 v[24:27], v[202:205], v[24:27], v[32:35]
	v_mfma_f32_16x16x32_bf16 v[116:119], v[228:231], v[28:31], v[24:27]
	v_mfma_f32_16x16x32_bf16 v[24:27], v[178:181], v[60:63], v[36:39]
	v_mfma_f32_16x16x32_bf16 v[96:99], v[198:201], v[100:103], v[24:27]
	v_mfma_f32_16x16x32_bf16 v[24:27], v[202:205], v[60:63], v[40:43]
	v_mfma_f32_16x16x32_bf16 v[100:103], v[228:231], v[100:103], v[24:27]
	v_mfma_f32_16x16x32_bf16 v[24:27], v[178:181], v[232:235], v[44:47]
	v_mfma_f32_16x16x32_bf16 v[80:83], v[198:201], v[236:239], v[24:27]
	v_mfma_f32_16x16x32_bf16 v[24:27], v[202:205], v[232:235], v[48:51]
	v_mfma_f32_16x16x32_bf16 v[84:87], v[228:231], v[236:239], v[24:27]
	v_mfma_f32_16x16x32_bf16 v[24:27], v[178:181], v[240:243], v[52:55]
	v_mfma_f32_16x16x32_bf16 v[112:115], v[198:201], v[28:31], v[64:67]
	v_mfma_f32_16x16x32_bf16 v[64:67], v[198:201], v[244:247], v[24:27]
	v_mfma_f32_16x16x32_bf16 v[24:27], v[202:205], v[240:243], v[56:59]
	v_mfma_f32_16x16x32_bf16 v[68:71], v[228:231], v[244:247], v[24:27]
	s_setprio 0
	s_barrier
	s_mov_b32 m0, s83
	s_nop 3
	v_lshl_add_u64 v[24:25], v[144:145], 0, s[14:15]
	s_add_u32 s52, s64, 0x10080
	ds_read_b128 v[32:35], v151 offset:49152
	ds_read_b128 v[36:39], v151 offset:50176
	ds_read_b128 v[214:217], v151 offset:51200
	ds_read_b128 v[218:221], v151 offset:52224
	ds_read_b128 v[232:235], v151 offset:53248
	ds_read_b128 v[236:239], v151 offset:54272
	ds_read_b128 v[240:243], v151 offset:55296
	ds_read_b128 v[244:247], v151 offset:56320
	global_load_lds_dwordx4 v[24:25], off
	v_lshl_add_u64 v[24:25], v[248:249], 0, s[14:15]
	s_mov_b32 m0, s35
	s_addc_u32 s53, s65, 0
	global_load_lds_dwordx4 v[24:25], off
	v_lshl_add_u64 v[24:25], s[52:53], 0, v[132:133]
	s_mov_b32 m0, s37
	s_nop 0
	global_load_lds_dwordx4 v[24:25], off
	v_lshl_add_u64 v[24:25], s[52:53], 0, v[128:129]
	s_mov_b32 m0, s62
	s_nop 0
	global_load_lds_dwordx4 v[24:25], off
	v_lshl_add_u64 v[24:25], v[250:251], 0, s[14:15]
	s_mov_b32 m0, s70
	s_nop 0
	global_load_lds_dwordx4 v[24:25], off
	v_lshl_add_u64 v[24:25], v[252:253], 0, s[14:15]
	s_mov_b32 m0, s71
	s_nop 0
	global_load_lds_dwordx4 v[24:25], off
	s_waitcnt vmcnt(8)
	s_waitcnt lgkmcnt(0)
	s_barrier
	s_setprio 1
	s_waitcnt lgkmcnt(0)
	v_mfma_f32_16x16x32_bf16 v[24:27], v[8:11], v[32:35], v[140:143]
	v_mfma_f32_16x16x32_bf16 v[60:63], v[12:15], v[36:39], v[24:27]
	v_mfma_f32_16x16x32_bf16 v[24:27], v[16:19], v[32:35], v[154:157]
	v_mfma_f32_16x16x32_bf16 v[56:59], v[20:23], v[36:39], v[24:27]
	v_mfma_f32_16x16x32_bf16 v[24:27], v[8:11], v[214:217], v[158:161]
	v_mfma_f32_16x16x32_bf16 v[44:47], v[12:15], v[218:221], v[24:27]
	v_mfma_f32_16x16x32_bf16 v[24:27], v[16:19], v[214:217], v[162:165]
	v_mfma_f32_16x16x32_bf16 v[40:43], v[20:23], v[218:221], v[24:27]
	v_mfma_f32_16x16x32_bf16 v[24:27], v[8:11], v[232:235], v[166:169]
	v_mfma_f32_16x16x32_bf16 v[0:3], v[8:11], v[240:243], v[0:3]
	v_mfma_f32_16x16x32_bf16 v[28:31], v[12:15], v[236:239], v[24:27]
	v_mfma_f32_16x16x32_bf16 v[24:27], v[16:19], v[232:235], v[170:173]
	v_mfma_f32_16x16x32_bf16 v[12:15], v[12:15], v[244:247], v[0:3]
	v_mfma_f32_16x16x32_bf16 v[0:3], v[16:19], v[240:243], v[4:7]
	v_mfma_f32_16x16x32_bf16 v[24:27], v[20:23], v[236:239], v[24:27]
	v_mfma_f32_16x16x32_bf16 v[8:11], v[20:23], v[244:247], v[0:3]
	s_setprio 0
	s_setprio 1
	v_mfma_f32_16x16x32_bf16 v[0:3], v[178:181], v[32:35], v[206:209]
	v_mfma_f32_16x16x32_bf16 v[48:51], v[198:201], v[36:39], v[0:3]
	v_mfma_f32_16x16x32_bf16 v[0:3], v[202:205], v[32:35], v[210:213]
	v_mfma_f32_16x16x32_bf16 v[52:55], v[228:231], v[36:39], v[0:3]
	v_mfma_f32_16x16x32_bf16 v[0:3], v[178:181], v[214:217], v[222:225]
	v_mfma_f32_16x16x32_bf16 v[32:35], v[198:201], v[218:221], v[0:3]
	v_mfma_f32_16x16x32_bf16 v[0:3], v[202:205], v[214:217], v[182:185]
	v_mfma_f32_16x16x32_bf16 v[36:39], v[228:231], v[218:221], v[0:3]
	v_mfma_f32_16x16x32_bf16 v[0:3], v[178:181], v[232:235], v[186:189]
	v_mfma_f32_16x16x32_bf16 v[16:19], v[198:201], v[236:239], v[0:3]
	v_mfma_f32_16x16x32_bf16 v[0:3], v[202:205], v[232:235], v[190:193]
	v_mfma_f32_16x16x32_bf16 v[20:23], v[228:231], v[236:239], v[0:3]
	v_mfma_f32_16x16x32_bf16 v[0:3], v[178:181], v[240:243], v[194:197]
	v_mfma_f32_16x16x32_bf16 v[4:7], v[198:201], v[244:247], v[0:3]
	v_mfma_f32_16x16x32_bf16 v[0:3], v[202:205], v[240:243], v[174:177]
	v_mfma_f32_16x16x32_bf16 v[0:3], v[228:231], v[244:247], v[0:3]
	s_setprio 0
	s_barrier
	s_andn2_b64 vcc, exec, s[16:17]
	s_cbranch_vccnz .LBB0_1356
	s_barrier

; #define PG8_STAGE(bufoff, gbase, voff) do { _Pragma("unroll") for (int _i = 0; _i < 2; ++_i) \
;         __builtin_amdgcn_global_load_lds((const unsigned*)((const char*)(gbase) + (voff)[_i]), (PG8_LAS unsigned*)(lds + (bufoff) + ldsw + _i * 8192), 16, 0, 0); } while (0)
; #define PG8_LDA(dst, b, h) do { _Pragma("unroll") for (int m = 0; m < 4; ++m) _Pragma("unroll") for (int k = 0; k < 2; ++k) dst[m][k] = *(const PG8_LAS bf16x8*)(lds + PG8_SA(b, h) + aoff + m * 2048 + k * 1024); } while (0)
; #define PG8_MMA(ai, bj, At, Bt) do { __builtin_amdgcn_s_setprio(1); _Pragma("unroll") for (int m = 0; m < 4; ++m) _Pragma("unroll") for (int n = 0; n < 2; ++n) _Pragma("unroll") for (int k = 0; k < 2; ++k) \
;         acc[ai][bj][m][n] = __builtin_amdgcn_mfma_f32_16x16x32_bf16(Bt[n][k], At[m][k], acc[ai][bj][m][n], 0, 0, 0); __builtin_amdgcn_s_setprio(0); } while (0)
; #define PG8_WAIT_V(n) asm volatile("s_waitcnt vmcnt(" #n ")" ::: "memory")
; #define PG8_WAIT_L(n) asm volatile("s_waitcnt lgkmcnt(" #n ")" ::: "memory")
; #define PG8_BAR __builtin_amdgcn_s_barrier()
; #define PG8_SCHED __builtin_amdgcn_sched_barrier(0)
; template <class Epi, class Sched, bool ALIGN_EPI = false, bool SP2 = false>
; __device__ __forceinline__ void gemm_phase(PG8_LAS unsigned char* lds, const Gemm g, const Sched& S, const Epi& E) {
;     ...
;             PG8_WAIT_V(8); PG8_WAIT_L(0); PG8_BAR; PG8_MMA(0, 0, At, B0); PG8_MMA(0, 1, At, B1); PG8_BAR; PG8_SCHED;
;             PG8_LDA(At, 0, 1); PG8_STAGE(PG8_SB(0, 0), b2, voffB); PG8_STAGE(PG8_SB(0, 1), b2 + hstep, voffB); PG8_STAGE(PG8_SA(0, 0), a2, voffA);
.Lrj_P4_0:
	s_waitcnt lgkmcnt(0)
	s_barrier
	s_setprio 1
	s_waitcnt lgkmcnt(0)
	v_mfma_f32_16x16x32_bf16 v[140:143], v[56:59], v[186:189], v[140:143]
	v_mfma_f32_16x16x32_bf16 v[136:139], v[72:75], v[186:189], v[136:139]
	v_mfma_f32_16x16x32_bf16 v[120:123], v[72:75], v[194:197], v[120:123]
	v_mfma_f32_16x16x32_bf16 v[124:127], v[56:59], v[194:197], v[124:127]
	v_mfma_f32_16x16x32_bf16 v[108:111], v[56:59], v[202:205], v[108:111]
	v_mfma_f32_16x16x32_bf16 v[104:107], v[72:75], v[202:205], v[104:107]
	v_mfma_f32_16x16x32_bf16 v[88:91], v[72:75], v[210:213], v[88:91]
	v_mfma_f32_16x16x32_bf16 v[92:95], v[56:59], v[210:213], v[92:95]
	v_mfma_f32_16x16x32_bf16 v[140:143], v[60:63], v[190:193], v[140:143]
	v_mfma_f32_16x16x32_bf16 v[136:139], v[76:79], v[190:193], v[136:139]
	v_mfma_f32_16x16x32_bf16 v[120:123], v[76:79], v[198:201], v[120:123]
	v_mfma_f32_16x16x32_bf16 v[124:127], v[60:63], v[198:201], v[124:127]
	v_mfma_f32_16x16x32_bf16 v[108:111], v[60:63], v[206:209], v[108:111]
	v_mfma_f32_16x16x32_bf16 v[104:107], v[76:79], v[206:209], v[104:107]
	v_mfma_f32_16x16x32_bf16 v[88:91], v[76:79], v[214:217], v[88:91]
	v_mfma_f32_16x16x32_bf16 v[92:95], v[60:63], v[214:217], v[92:95]
	s_setprio 0
	s_setprio 1
	v_mfma_f32_16x16x32_bf16 v[132:135], v[162:165], v[186:189], v[132:135]
	v_mfma_f32_16x16x32_bf16 v[128:131], v[178:181], v[186:189], v[128:131]
	v_mfma_f32_16x16x32_bf16 v[112:115], v[178:181], v[194:197], v[112:115]
	v_mfma_f32_16x16x32_bf16 v[116:119], v[162:165], v[194:197], v[116:119]
	v_mfma_f32_16x16x32_bf16 v[100:103], v[162:165], v[202:205], v[100:103]
	v_mfma_f32_16x16x32_bf16 v[96:99], v[178:181], v[202:205], v[96:99]
	v_mfma_f32_16x16x32_bf16 v[80:83], v[178:181], v[210:213], v[80:83]
	v_mfma_f32_16x16x32_bf16 v[84:87], v[162:165], v[210:213], v[84:87]
	v_mfma_f32_16x16x32_bf16 v[132:135], v[166:169], v[190:193], v[132:135]
	v_mfma_f32_16x16x32_bf16 v[128:131], v[182:185], v[190:193], v[128:131]
	v_mfma_f32_16x16x32_bf16 v[112:115], v[182:185], v[198:201], v[112:115]
	v_mfma_f32_16x16x32_bf16 v[116:119], v[166:169], v[198:201], v[116:119]
	v_mfma_f32_16x16x32_bf16 v[100:103], v[166:169], v[206:209], v[100:103]
	v_mfma_f32_16x16x32_bf16 v[96:99], v[182:185], v[206:209], v[96:99]
	v_mfma_f32_16x16x32_bf16 v[80:83], v[182:185], v[214:217], v[80:83]
	v_mfma_f32_16x16x32_bf16 v[84:87], v[166:169], v[214:217], v[84:87]
	s_setprio 0
	s_barrier
	s_add_i32 s76, s64, s41
	v_lshl_add_u64 v[218:219], s[36:37], 0, v[146:147]
	s_mov_b32 m0, s76
	ds_read_b128 v[186:189], v175 offset:16384
	ds_read_b128 v[190:193], v175 offset:17408
	ds_read_b128 v[194:197], v175 offset:18432
	ds_read_b128 v[198:201], v175 offset:19456
	ds_read_b128 v[202:205], v175 offset:20480
	ds_read_b128 v[206:209], v175 offset:21504
	ds_read_b128 v[210:213], v175 offset:22528
	ds_read_b128 v[214:217], v175 offset:23552
	global_load_lds_dwordx4 v[218:219], off
	s_add_i32 m0, s76, 0x2000
	s_add_u32 s76, s36, 0x40000
	v_lshl_add_u64 v[220:221], s[36:37], 0, v[150:151]
	s_addc_u32 s77, s37, 0
	s_add_i32 s80, s65, s41
	global_load_lds_dwordx4 v[220:221], off
	v_lshl_add_u64 v[222:223], s[76:77], 0, v[146:147]
	s_mov_b32 m0, s80
	v_lshl_add_u64 v[224:225], s[38:39], 0, v[148:149]
	global_load_lds_dwordx4 v[222:223], off
	v_lshl_add_u64 v[222:223], s[76:77], 0, v[150:151]
	s_add_i32 m0, s80, 0x2000
	s_nop 0
	global_load_lds_dwordx4 v[222:223], off
	v_lshl_add_u64 v[222:223], s[38:39], 0, v[144:145]
	s_mov_b32 m0, s42
	s_nop 0
	global_load_lds_dwordx4 v[222:223], off
	s_mov_b32 m0, s43
	s_nop 0
	global_load_lds_dwordx4 v[224:225], off
	s_cmp_eq_u32 s99, 1
	s_cbranch_scc1 .Lrw_P4_1
	s_waitcnt vmcnt(8)
	s_branch .Lrj_P4_1

; #define PG8_STAGE(bufoff, gbase, voff) do { _Pragma("unroll") for (int _i = 0; _i < 2; ++_i) \
;         __builtin_amdgcn_global_load_lds((const unsigned*)((const char*)(gbase) + (voff)[_i]), (PG8_LAS unsigned*)(lds + (bufoff) + ldsw + _i * 8192), 16, 0, 0); } while (0)
; #define PG8_LDA(dst, b, h) do { _Pragma("unroll") for (int m = 0; m < 4; ++m) _Pragma("unroll") for (int k = 0; k < 2; ++k) dst[m][k] = *(const PG8_LAS bf16x8*)(lds + PG8_SA(b, h) + aoff + m * 2048 + k * 1024); } while (0)
; #define PG8_LDB(dst, b, h) do { _Pragma("unroll") for (int n = 0; n < 2; ++n) _Pragma("unroll") for (int k = 0; k < 2; ++k) dst[n][k] = *(const PG8_LAS bf16x8*)(lds + PG8_SB(b, h) + boff + n * 2048 + k * 1024); } while (0)
; #define PG8_MMA(ai, bj, At, Bt) do { __builtin_amdgcn_s_setprio(1); _Pragma("unroll") for (int m = 0; m < 4; ++m) _Pragma("unroll") for (int n = 0; n < 2; ++n) _Pragma("unroll") for (int k = 0; k < 2; ++k) \
;         acc[ai][bj][m][n] = __builtin_amdgcn_mfma_f32_16x16x32_bf16(Bt[n][k], At[m][k], acc[ai][bj][m][n], 0, 0, 0); __builtin_amdgcn_s_setprio(0); } while (0)
; #define PG8_WAIT_V(n) asm volatile("s_waitcnt vmcnt(" #n ")" ::: "memory")
; #define PG8_WAIT_L(n) asm volatile("s_waitcnt lgkmcnt(" #n ")" ::: "memory")
; #define PG8_BAR __builtin_amdgcn_s_barrier()
; #define PG8_SCHED __builtin_amdgcn_sched_barrier(0)
; template <class Epi, class Sched, bool ALIGN_EPI = false, bool SP2 = false>
; __device__ __forceinline__ void gemm_phase(PG8_LAS unsigned char* lds, const Gemm g, const Sched& S, const Epi& E) {
;     ...
;             PG8_WAIT_V(8); PG8_WAIT_L(0); PG8_BAR; PG8_MMA(1, 0, At, B0); PG8_MMA(1, 1, At, B1); PG8_BAR; PG8_SCHED;
;             PG8_LDB(B0, 1, 0); PG8_LDB(B1, 1, 1); PG8_SCHED; PG8_LDA(At, 1, 0); PG8_STAGE(PG8_SA(0, 1), a2 + hstep, voffA);
;             PG8_WAIT_V(8); PG8_WAIT_L(0); PG8_BAR; PG8_MMA(0, 0, At, B0); PG8_MMA(0, 1, At, B1); PG8_BAR; PG8_SCHED;
.Lrj_P4_1:
	s_waitcnt lgkmcnt(0)
	s_barrier
	s_setprio 1
	s_waitcnt lgkmcnt(0)
	v_mfma_f32_16x16x32_bf16 v[68:71], v[56:59], v[186:189], v[68:71]
	v_mfma_f32_16x16x32_bf16 v[64:67], v[72:75], v[186:189], v[64:67]
	v_mfma_f32_16x16x32_bf16 v[40:43], v[72:75], v[194:197], v[40:43]
	v_mfma_f32_16x16x32_bf16 v[44:47], v[56:59], v[194:197], v[44:47]
	v_mfma_f32_16x16x32_bf16 v[28:31], v[56:59], v[202:205], v[28:31]
	v_mfma_f32_16x16x32_bf16 v[24:27], v[72:75], v[202:205], v[24:27]
	v_mfma_f32_16x16x32_bf16 v[8:11], v[72:75], v[210:213], v[8:11]
	v_mfma_f32_16x16x32_bf16 v[12:15], v[56:59], v[210:213], v[12:15]
	v_mfma_f32_16x16x32_bf16 v[68:71], v[60:63], v[190:193], v[68:71]
	v_mfma_f32_16x16x32_bf16 v[64:67], v[76:79], v[190:193], v[64:67]
	v_mfma_f32_16x16x32_bf16 v[40:43], v[76:79], v[198:201], v[40:43]
	v_mfma_f32_16x16x32_bf16 v[44:47], v[60:63], v[198:201], v[44:47]
	v_mfma_f32_16x16x32_bf16 v[28:31], v[60:63], v[206:209], v[28:31]
	v_mfma_f32_16x16x32_bf16 v[24:27], v[76:79], v[206:209], v[24:27]
	v_mfma_f32_16x16x32_bf16 v[8:11], v[76:79], v[214:217], v[8:11]
	v_mfma_f32_16x16x32_bf16 v[12:15], v[60:63], v[214:217], v[12:15]
	s_setprio 0
	s_setprio 1
	v_mfma_f32_16x16x32_bf16 v[52:55], v[162:165], v[186:189], v[52:55]
	v_mfma_f32_16x16x32_bf16 v[48:51], v[178:181], v[186:189], v[48:51]
	v_mfma_f32_16x16x32_bf16 v[32:35], v[178:181], v[194:197], v[32:35]
	v_mfma_f32_16x16x32_bf16 v[36:39], v[162:165], v[194:197], v[36:39]
	v_mfma_f32_16x16x32_bf16 v[20:23], v[162:165], v[202:205], v[20:23]
	v_mfma_f32_16x16x32_bf16 v[16:19], v[178:181], v[202:205], v[16:19]
	v_mfma_f32_16x16x32_bf16 v[0:3], v[178:181], v[210:213], v[0:3]
	v_mfma_f32_16x16x32_bf16 v[4:7], v[162:165], v[210:213], v[4:7]
	v_mfma_f32_16x16x32_bf16 v[52:55], v[166:169], v[190:193], v[52:55]
	v_mfma_f32_16x16x32_bf16 v[48:51], v[182:185], v[190:193], v[48:51]
	v_mfma_f32_16x16x32_bf16 v[32:35], v[182:185], v[198:201], v[32:35]
	v_mfma_f32_16x16x32_bf16 v[36:39], v[166:169], v[198:201], v[36:39]
	v_mfma_f32_16x16x32_bf16 v[20:23], v[166:169], v[206:209], v[20:23]
	v_mfma_f32_16x16x32_bf16 v[16:19], v[182:185], v[206:209], v[16:19]
	v_mfma_f32_16x16x32_bf16 v[0:3], v[182:185], v[214:217], v[0:3]
	v_mfma_f32_16x16x32_bf16 v[4:7], v[166:169], v[214:217], v[4:7]
	s_setprio 0
	s_barrier
	s_add_i32 s76, 0, 0x18000
	s_add_i32 s77, 0, 0x1c000
	v_add_u32_e32 v76, s76, v171
	v_add_u32_e32 v152, s77, v171
	ds_read_b128 v[56:59], v76
	ds_read_b128 v[60:63], v76 offset:1024
	ds_read_b128 v[72:75], v76 offset:2048
	ds_read_b128 v[76:79], v76 offset:3072
	ds_read_b128 v[162:165], v152
	ds_read_b128 v[166:169], v152 offset:1024
	ds_read_b128 v[178:181], v152 offset:2048
	ds_read_b128 v[182:185], v152 offset:3072
	s_add_u32 s38, s38, 0x40000
	s_addc_u32 s39, s39, 0
	s_mov_b32 m0, s46
	v_lshl_add_u64 v[228:229], s[38:39], 0, v[144:145]
	ds_read_b128 v[186:189], v175 offset:32768
	ds_read_b128 v[190:193], v175 offset:33792
	ds_read_b128 v[194:197], v175 offset:34816
	ds_read_b128 v[198:201], v175 offset:35840
	ds_read_b128 v[202:205], v175 offset:36864
	ds_read_b128 v[206:209], v175 offset:37888
	ds_read_b128 v[210:213], v175 offset:38912
	ds_read_b128 v[214:217], v175 offset:39936
	global_load_lds_dwordx4 v[228:229], off
	v_lshl_add_u64 v[228:229], s[38:39], 0, v[148:149]
	s_mov_b32 m0, s47
	s_nop 0
	global_load_lds_dwordx4 v[228:229], off
	s_waitcnt vmcnt(8)
	s_waitcnt lgkmcnt(0)
	s_barrier
	s_setprio 1
	s_waitcnt lgkmcnt(0)
	v_mfma_f32_16x16x32_bf16 v[140:143], v[56:59], v[186:189], v[140:143]
	v_mfma_f32_16x16x32_bf16 v[136:139], v[72:75], v[186:189], v[136:139]
	v_mfma_f32_16x16x32_bf16 v[120:123], v[72:75], v[194:197], v[120:123]
	v_mfma_f32_16x16x32_bf16 v[124:127], v[56:59], v[194:197], v[124:127]
	v_mfma_f32_16x16x32_bf16 v[108:111], v[56:59], v[202:205], v[108:111]
	v_mfma_f32_16x16x32_bf16 v[104:107], v[72:75], v[202:205], v[104:107]
	v_mfma_f32_16x16x32_bf16 v[88:91], v[72:75], v[210:213], v[88:91]
	v_mfma_f32_16x16x32_bf16 v[92:95], v[56:59], v[210:213], v[92:95]
	v_mfma_f32_16x16x32_bf16 v[140:143], v[60:63], v[190:193], v[140:143]
	v_mfma_f32_16x16x32_bf16 v[136:139], v[76:79], v[190:193], v[136:139]
	v_mfma_f32_16x16x32_bf16 v[120:123], v[76:79], v[198:201], v[120:123]
	v_mfma_f32_16x16x32_bf16 v[124:127], v[60:63], v[198:201], v[124:127]
	v_mfma_f32_16x16x32_bf16 v[108:111], v[60:63], v[206:209], v[108:111]
	v_mfma_f32_16x16x32_bf16 v[104:107], v[76:79], v[206:209], v[104:107]
	v_mfma_f32_16x16x32_bf16 v[88:91], v[76:79], v[214:217], v[88:91]
	v_mfma_f32_16x16x32_bf16 v[92:95], v[60:63], v[214:217], v[92:95]
	s_setprio 0
	s_setprio 1
	v_mfma_f32_16x16x32_bf16 v[132:135], v[162:165], v[186:189], v[132:135]
	v_mfma_f32_16x16x32_bf16 v[128:131], v[178:181], v[186:189], v[128:131]
	v_mfma_f32_16x16x32_bf16 v[112:115], v[178:181], v[194:197], v[112:115]
	v_mfma_f32_16x16x32_bf16 v[116:119], v[162:165], v[194:197], v[116:119]
	v_mfma_f32_16x16x32_bf16 v[100:103], v[162:165], v[202:205], v[100:103]
	v_mfma_f32_16x16x32_bf16 v[96:99], v[178:181], v[202:205], v[96:99]
	v_mfma_f32_16x16x32_bf16 v[80:83], v[178:181], v[210:213], v[80:83]
	v_mfma_f32_16x16x32_bf16 v[84:87], v[162:165], v[210:213], v[84:87]
	v_mfma_f32_16x16x32_bf16 v[132:135], v[166:169], v[190:193], v[132:135]
	v_mfma_f32_16x16x32_bf16 v[128:131], v[182:185], v[190:193], v[128:131]
	v_mfma_f32_16x16x32_bf16 v[112:115], v[182:185], v[198:201], v[112:115]
	v_mfma_f32_16x16x32_bf16 v[116:119], v[166:169], v[198:201], v[116:119]
	v_mfma_f32_16x16x32_bf16 v[100:103], v[166:169], v[206:209], v[100:103]
	v_mfma_f32_16x16x32_bf16 v[96:99], v[182:185], v[206:209], v[96:99]
	v_mfma_f32_16x16x32_bf16 v[80:83], v[182:185], v[214:217], v[80:83]
	v_mfma_f32_16x16x32_bf16 v[84:87], v[166:169], v[214:217], v[84:87]
	s_setprio 0
	s_barrier
; #define PG8_STAGE(bufoff, gbase, voff) do { _Pragma("unroll") for (int _i = 0; _i < 2; ++_i) \
;         __builtin_amdgcn_global_load_lds((const unsigned*)((const char*)(gbase) + (voff)[_i]), (PG8_LAS unsigned*)(lds + (bufoff) + ldsw + _i * 8192), 16, 0, 0); } while (0)
; #define PG8_LDA(dst, b, h) do { _Pragma("unroll") for (int m = 0; m < 4; ++m) _Pragma("unroll") for (int k = 0; k < 2; ++k) dst[m][k] = *(const PG8_LAS bf16x8*)(lds + PG8_SA(b, h) + aoff + m * 2048 + k * 1024); } while (0)
; #define PG8_MMA(ai, bj, At, Bt) do { __builtin_amdgcn_s_setprio(1); _Pragma("unroll") for (int m = 0; m < 4; ++m) _Pragma("unroll") for (int n = 0; n < 2; ++n) _Pragma("unroll") for (int k = 0; k < 2; ++k) \
;         acc[ai][bj][m][n] = __builtin_amdgcn_mfma_f32_16x16x32_bf16(Bt[n][k], At[m][k], acc[ai][bj][m][n], 0, 0, 0); __builtin_amdgcn_s_setprio(0); } while (0)
; #define PG8_WAIT_V(n) asm volatile("s_waitcnt vmcnt(" #n ")" ::: "memory")
; #define PG8_WAIT_L(n) asm volatile("s_waitcnt lgkmcnt(" #n ")" ::: "memory")
; #define PG8_BAR __builtin_amdgcn_s_barrier()
; #define PG8_SCHED __builtin_amdgcn_sched_barrier(0)
; template <class Epi, class Sched, bool ALIGN_EPI = false, bool SP2 = false>
; __device__ __forceinline__ void gemm_phase(PG8_LAS unsigned char* lds, const Gemm g, const Sched& S, const Epi& E) {
;     ...
;             PG8_LDA(At, 1, 1); PG8_STAGE(PG8_SB(1, 0), b3, voffB); PG8_STAGE(PG8_SB(1, 1), b3 + hstep, voffB); PG8_STAGE(PG8_SA(1, 0), a3, voffA);
;             PG8_WAIT_V(8); PG8_WAIT_L(0); PG8_BAR; PG8_MMA(1, 0, At, B0); PG8_MMA(1, 1, At, B1); PG8_BAR; PG8_SCHED;
;     ...
;         if constexpr (ALIGN_EPI) { if (wr == 0) PG8_BAR; }
	s_add_i32 s38, s76, s41
	v_lshl_add_u64 v[218:219], v[218:219], 0, s[18:19]
	s_mov_b32 m0, s38
	ds_read_b128 v[186:189], v175 offset:49152
	ds_read_b128 v[190:193], v175 offset:50176
	ds_read_b128 v[194:197], v175 offset:51200
	ds_read_b128 v[198:201], v175 offset:52224
	ds_read_b128 v[202:205], v175 offset:53248
	ds_read_b128 v[206:209], v175 offset:54272
	ds_read_b128 v[210:213], v175 offset:55296
	ds_read_b128 v[214:217], v175 offset:56320
	global_load_lds_dwordx4 v[218:219], off
	s_add_i32 m0, s38, 0x2000
	s_add_u32 s36, s36, 0x40080
	v_lshl_add_u64 v[218:219], v[220:221], 0, s[18:19]
	s_addc_u32 s37, s37, 0
	s_add_i32 s38, s77, s41
	global_load_lds_dwordx4 v[218:219], off
	v_lshl_add_u64 v[218:219], s[36:37], 0, v[146:147]
	s_mov_b32 m0, s38
	s_nop 0
	global_load_lds_dwordx4 v[218:219], off
	v_lshl_add_u64 v[218:219], s[36:37], 0, v[150:151]
	s_add_i32 m0, s38, 0x2000
	s_nop 0
	global_load_lds_dwordx4 v[218:219], off
	v_lshl_add_u64 v[218:219], v[222:223], 0, s[18:19]
	s_mov_b32 m0, s53
	s_nop 0
	global_load_lds_dwordx4 v[218:219], off
	v_lshl_add_u64 v[218:219], v[224:225], 0, s[18:19]
	s_mov_b32 m0, s60
	s_nop 0
	global_load_lds_dwordx4 v[218:219], off
	s_waitcnt vmcnt(8)
	s_waitcnt lgkmcnt(0)
	s_barrier
	s_setprio 1
	s_waitcnt lgkmcnt(0)
	v_mfma_f32_16x16x32_bf16 v[68:71], v[56:59], v[186:189], v[68:71]
	v_mfma_f32_16x16x32_bf16 v[64:67], v[72:75], v[186:189], v[64:67]
	v_mfma_f32_16x16x32_bf16 v[40:43], v[72:75], v[194:197], v[40:43]
	v_mfma_f32_16x16x32_bf16 v[44:47], v[56:59], v[194:197], v[44:47]
	v_mfma_f32_16x16x32_bf16 v[28:31], v[56:59], v[202:205], v[28:31]
	v_mfma_f32_16x16x32_bf16 v[24:27], v[72:75], v[202:205], v[24:27]
	v_mfma_f32_16x16x32_bf16 v[8:11], v[72:75], v[210:213], v[8:11]
	v_mfma_f32_16x16x32_bf16 v[12:15], v[56:59], v[210:213], v[12:15]
	v_mfma_f32_16x16x32_bf16 v[68:71], v[60:63], v[190:193], v[68:71]
	v_mfma_f32_16x16x32_bf16 v[64:67], v[76:79], v[190:193], v[64:67]
	v_mfma_f32_16x16x32_bf16 v[40:43], v[76:79], v[198:201], v[40:43]
	v_mfma_f32_16x16x32_bf16 v[44:47], v[60:63], v[198:201], v[44:47]
	v_mfma_f32_16x16x32_bf16 v[28:31], v[60:63], v[206:209], v[28:31]
	v_mfma_f32_16x16x32_bf16 v[24:27], v[76:79], v[206:209], v[24:27]
	v_mfma_f32_16x16x32_bf16 v[8:11], v[76:79], v[214:217], v[8:11]
	v_mfma_f32_16x16x32_bf16 v[12:15], v[60:63], v[214:217], v[12:15]
	s_setprio 0
	s_setprio 1
	v_mfma_f32_16x16x32_bf16 v[52:55], v[162:165], v[186:189], v[52:55]
	v_mfma_f32_16x16x32_bf16 v[48:51], v[178:181], v[186:189], v[48:51]
	v_mfma_f32_16x16x32_bf16 v[32:35], v[178:181], v[194:197], v[32:35]
	v_mfma_f32_16x16x32_bf16 v[36:39], v[162:165], v[194:197], v[36:39]
	v_mfma_f32_16x16x32_bf16 v[20:23], v[162:165], v[202:205], v[20:23]
	v_mfma_f32_16x16x32_bf16 v[16:19], v[178:181], v[202:205], v[16:19]
	v_mfma_f32_16x16x32_bf16 v[0:3], v[178:181], v[210:213], v[0:3]
	v_mfma_f32_16x16x32_bf16 v[4:7], v[162:165], v[210:213], v[4:7]
	v_mfma_f32_16x16x32_bf16 v[52:55], v[166:169], v[190:193], v[52:55]
	v_mfma_f32_16x16x32_bf16 v[48:51], v[182:185], v[190:193], v[48:51]
	v_mfma_f32_16x16x32_bf16 v[32:35], v[182:185], v[198:201], v[32:35]
	v_mfma_f32_16x16x32_bf16 v[36:39], v[166:169], v[198:201], v[36:39]
	v_mfma_f32_16x16x32_bf16 v[20:23], v[166:169], v[206:209], v[20:23]
	v_mfma_f32_16x16x32_bf16 v[16:19], v[182:185], v[206:209], v[16:19]
	v_mfma_f32_16x16x32_bf16 v[0:3], v[182:185], v[214:217], v[0:3]
	v_mfma_f32_16x16x32_bf16 v[4:7], v[166:169], v[214:217], v[4:7]
	s_setprio 0
	s_barrier
	s_mov_b32 s99, 0
	s_add_i32 s75, s75, 2
	s_add_u32 s34, s34, 0x100
	s_addc_u32 s35, s35, 0
	s_add_u32 s73, s73, 0x100
	s_addc_u32 s74, s74, 0
	s_cmp_gt_u32 s75, 13
	s_cbranch_scc0 .LBB0_1423
	s_and_b64 vcc, exec, s[20:21]
	s_cbranch_vccz .LBB0_1426
	s_barrier

; #define PG8_STAGE(bufoff, gbase, voff) do { _Pragma("unroll") for (int _i = 0; _i < 2; ++_i) \
;         __builtin_amdgcn_global_load_lds((const unsigned*)((const char*)(gbase) + (voff)[_i]), (PG8_LAS unsigned*)(lds + (bufoff) + ldsw + _i * 8192), 16, 0, 0); } while (0)
; #define PG8_LDA(dst, b, h) do { _Pragma("unroll") for (int m = 0; m < 4; ++m) _Pragma("unroll") for (int k = 0; k < 2; ++k) dst[m][k] = *(const PG8_LAS bf16x8*)(lds + PG8_SA(b, h) + aoff + m * 2048 + k * 1024); } while (0)
; #define PG8_MMA(ai, bj, At, Bt) do { __builtin_amdgcn_s_setprio(1); _Pragma("unroll") for (int m = 0; m < 4; ++m) _Pragma("unroll") for (int n = 0; n < 2; ++n) _Pragma("unroll") for (int k = 0; k < 2; ++k) \
;         acc[ai][bj][m][n] = __builtin_amdgcn_mfma_f32_16x16x32_bf16(Bt[n][k], At[m][k], acc[ai][bj][m][n], 0, 0, 0); __builtin_amdgcn_s_setprio(0); } while (0)
; #define PG8_WAIT_V(n) asm volatile("s_waitcnt vmcnt(" #n ")" ::: "memory")
; #define PG8_WAIT_L(n) asm volatile("s_waitcnt lgkmcnt(" #n ")" ::: "memory")
; #define PG8_BAR __builtin_amdgcn_s_barrier()
; #define PG8_SCHED __builtin_amdgcn_sched_barrier(0)
; template <class Epi, class Sched, bool ALIGN_EPI = false, bool SP2 = false>
; __device__ __forceinline__ void gemm_phase(PG8_LAS unsigned char* lds, const Gemm g, const Sched& S, const Epi& E) {
;     ...
;             PG8_WAIT_V(8); PG8_WAIT_L(0); PG8_BAR; PG8_MMA(0, 0, At, B0); PG8_MMA(0, 1, At, B1); PG8_BAR; PG8_SCHED;
;             PG8_LDA(At, 0, 1); PG8_STAGE(PG8_SB(0, 0), b2, voffB); PG8_STAGE(PG8_SB(0, 1), b2 + hstep, voffB); PG8_STAGE(PG8_SA(0, 0), a2, voffA);
.Lrj_P5_0:
	s_waitcnt lgkmcnt(0)
	s_barrier
	s_setprio 1
	s_waitcnt lgkmcnt(0)
	v_mfma_f32_16x16x32_bf16 v[124:127], v[144:147], v[184:187], v[124:127]
	v_mfma_f32_16x16x32_bf16 v[120:123], v[160:163], v[184:187], v[120:123]
	v_mfma_f32_16x16x32_bf16 v[104:107], v[160:163], v[192:195], v[104:107]
	v_mfma_f32_16x16x32_bf16 v[108:111], v[144:147], v[192:195], v[108:111]
	v_mfma_f32_16x16x32_bf16 v[92:95], v[144:147], v[200:203], v[92:95]
	v_mfma_f32_16x16x32_bf16 v[88:91], v[160:163], v[200:203], v[88:91]
	v_mfma_f32_16x16x32_bf16 v[72:75], v[160:163], v[208:211], v[72:75]
	v_mfma_f32_16x16x32_bf16 v[76:79], v[144:147], v[208:211], v[76:79]
	v_mfma_f32_16x16x32_bf16 v[124:127], v[156:159], v[188:191], v[124:127]
	v_mfma_f32_16x16x32_bf16 v[120:123], v[164:167], v[188:191], v[120:123]
	v_mfma_f32_16x16x32_bf16 v[104:107], v[164:167], v[196:199], v[104:107]
	v_mfma_f32_16x16x32_bf16 v[108:111], v[156:159], v[196:199], v[108:111]
	v_mfma_f32_16x16x32_bf16 v[92:95], v[156:159], v[204:207], v[92:95]
	v_mfma_f32_16x16x32_bf16 v[88:91], v[164:167], v[204:207], v[88:91]
	v_mfma_f32_16x16x32_bf16 v[72:75], v[164:167], v[212:215], v[72:75]
	v_mfma_f32_16x16x32_bf16 v[76:79], v[156:159], v[212:215], v[76:79]
	s_setprio 0
	s_setprio 1
	v_mfma_f32_16x16x32_bf16 v[116:119], v[168:171], v[184:187], v[116:119]
	v_mfma_f32_16x16x32_bf16 v[112:115], v[176:179], v[184:187], v[112:115]
	v_mfma_f32_16x16x32_bf16 v[96:99], v[176:179], v[192:195], v[96:99]
	v_mfma_f32_16x16x32_bf16 v[100:103], v[168:171], v[192:195], v[100:103]
	v_mfma_f32_16x16x32_bf16 v[84:87], v[168:171], v[200:203], v[84:87]
	v_mfma_f32_16x16x32_bf16 v[80:83], v[176:179], v[200:203], v[80:83]
	v_mfma_f32_16x16x32_bf16 v[64:67], v[176:179], v[208:211], v[64:67]
	v_mfma_f32_16x16x32_bf16 v[68:71], v[168:171], v[208:211], v[68:71]
	v_mfma_f32_16x16x32_bf16 v[116:119], v[172:175], v[188:191], v[116:119]
	v_mfma_f32_16x16x32_bf16 v[112:115], v[180:183], v[188:191], v[112:115]
	v_mfma_f32_16x16x32_bf16 v[96:99], v[180:183], v[196:199], v[96:99]
	v_mfma_f32_16x16x32_bf16 v[100:103], v[172:175], v[196:199], v[100:103]
	v_mfma_f32_16x16x32_bf16 v[84:87], v[172:175], v[204:207], v[84:87]
	v_mfma_f32_16x16x32_bf16 v[80:83], v[180:183], v[204:207], v[80:83]
	v_mfma_f32_16x16x32_bf16 v[64:67], v[180:183], v[212:215], v[64:67]
	v_mfma_f32_16x16x32_bf16 v[68:71], v[172:175], v[212:215], v[68:71]
	s_setprio 0
	s_barrier
	s_add_i32 s66, s52, s39
	v_lshl_add_u64 v[216:217], s[34:35], 0, v[132:133]
	s_mov_b32 m0, s66
	ds_read_b128 v[184:187], v153 offset:16384
	ds_read_b128 v[188:191], v153 offset:17408
	ds_read_b128 v[192:195], v153 offset:18432
	ds_read_b128 v[196:199], v153 offset:19456
	ds_read_b128 v[200:203], v153 offset:20480
	ds_read_b128 v[204:207], v153 offset:21504
	ds_read_b128 v[208:211], v153 offset:22528
	ds_read_b128 v[212:215], v153 offset:23552
	global_load_lds_dwordx4 v[216:217], off
	s_add_i32 m0, s66, 0x2000
	s_add_u32 s66, s34, 0x40000
	v_lshl_add_u64 v[218:219], s[34:35], 0, v[128:129]
	s_addc_u32 s67, s35, 0
	s_add_i32 s68, s53, s39
	global_load_lds_dwordx4 v[218:219], off
	v_lshl_add_u64 v[220:221], s[66:67], 0, v[132:133]
	s_mov_b32 m0, s68
	v_lshl_add_u64 v[222:223], s[36:37], 0, v[130:131]
	global_load_lds_dwordx4 v[220:221], off
	v_lshl_add_u64 v[220:221], s[66:67], 0, v[128:129]
	s_add_i32 m0, s68, 0x2000
	s_nop 0
	global_load_lds_dwordx4 v[220:221], off
	v_lshl_add_u64 v[220:221], s[36:37], 0, v[134:135]
	s_mov_b32 m0, s29
	s_nop 0
	global_load_lds_dwordx4 v[220:221], off
	s_mov_b32 m0, s42
	s_nop 0
	global_load_lds_dwordx4 v[222:223], off
	s_cmp_eq_u32 s99, 1
	s_cbranch_scc1 .Lrw_P5_1
	s_waitcnt vmcnt(8)
	s_branch .Lrj_P5_1

; #define PG8_STAGE(bufoff, gbase, voff) do { _Pragma("unroll") for (int _i = 0; _i < 2; ++_i) \
;         __builtin_amdgcn_global_load_lds((const unsigned*)((const char*)(gbase) + (voff)[_i]), (PG8_LAS unsigned*)(lds + (bufoff) + ldsw + _i * 8192), 16, 0, 0); } while (0)
; #define PG8_LDA(dst, b, h) do { _Pragma("unroll") for (int m = 0; m < 4; ++m) _Pragma("unroll") for (int k = 0; k < 2; ++k) dst[m][k] = *(const PG8_LAS bf16x8*)(lds + PG8_SA(b, h) + aoff + m * 2048 + k * 1024); } while (0)
; #define PG8_LDB(dst, b, h) do { _Pragma("unroll") for (int n = 0; n < 2; ++n) _Pragma("unroll") for (int k = 0; k < 2; ++k) dst[n][k] = *(const PG8_LAS bf16x8*)(lds + PG8_SB(b, h) + boff + n * 2048 + k * 1024); } while (0)
; #define PG8_MMA(ai, bj, At, Bt) do { __builtin_amdgcn_s_setprio(1); _Pragma("unroll") for (int m = 0; m < 4; ++m) _Pragma("unroll") for (int n = 0; n < 2; ++n) _Pragma("unroll") for (int k = 0; k < 2; ++k) \
;         acc[ai][bj][m][n] = __builtin_amdgcn_mfma_f32_16x16x32_bf16(Bt[n][k], At[m][k], acc[ai][bj][m][n], 0, 0, 0); __builtin_amdgcn_s_setprio(0); } while (0)
; #define PG8_WAIT_V(n) asm volatile("s_waitcnt vmcnt(" #n ")" ::: "memory")
; #define PG8_WAIT_L(n) asm volatile("s_waitcnt lgkmcnt(" #n ")" ::: "memory")
; #define PG8_BAR __builtin_amdgcn_s_barrier()
; #define PG8_SCHED __builtin_amdgcn_sched_barrier(0)
; template <class Epi, class Sched, bool ALIGN_EPI = false, bool SP2 = false>
; __device__ __forceinline__ void gemm_phase(PG8_LAS unsigned char* lds, const Gemm g, const Sched& S, const Epi& E) {
;     ...
;             PG8_WAIT_V(8); PG8_WAIT_L(0); PG8_BAR; PG8_MMA(1, 0, At, B0); PG8_MMA(1, 1, At, B1); PG8_BAR; PG8_SCHED;
;             PG8_LDB(B0, 1, 0); PG8_LDB(B1, 1, 1); PG8_SCHED; PG8_LDA(At, 1, 0); PG8_STAGE(PG8_SA(0, 1), a2 + hstep, voffA);
;             PG8_WAIT_V(8); PG8_WAIT_L(0); PG8_BAR; PG8_MMA(0, 0, At, B0); PG8_MMA(0, 1, At, B1); PG8_BAR; PG8_SCHED;
.Lrj_P5_1:
	s_waitcnt lgkmcnt(0)
	s_barrier
	s_setprio 1
	s_waitcnt lgkmcnt(0)
	v_mfma_f32_16x16x32_bf16 v[60:63], v[144:147], v[184:187], v[60:63]
	v_mfma_f32_16x16x32_bf16 v[56:59], v[160:163], v[184:187], v[56:59]
	v_mfma_f32_16x16x32_bf16 v[40:43], v[160:163], v[192:195], v[40:43]
	v_mfma_f32_16x16x32_bf16 v[44:47], v[144:147], v[192:195], v[44:47]
	v_mfma_f32_16x16x32_bf16 v[28:31], v[144:147], v[200:203], v[28:31]
	v_mfma_f32_16x16x32_bf16 v[24:27], v[160:163], v[200:203], v[24:27]
	v_mfma_f32_16x16x32_bf16 v[8:11], v[160:163], v[208:211], v[8:11]
	v_mfma_f32_16x16x32_bf16 v[12:15], v[144:147], v[208:211], v[12:15]
	v_mfma_f32_16x16x32_bf16 v[60:63], v[156:159], v[188:191], v[60:63]
	v_mfma_f32_16x16x32_bf16 v[56:59], v[164:167], v[188:191], v[56:59]
	v_mfma_f32_16x16x32_bf16 v[40:43], v[164:167], v[196:199], v[40:43]
	v_mfma_f32_16x16x32_bf16 v[44:47], v[156:159], v[196:199], v[44:47]
	v_mfma_f32_16x16x32_bf16 v[28:31], v[156:159], v[204:207], v[28:31]
	v_mfma_f32_16x16x32_bf16 v[24:27], v[164:167], v[204:207], v[24:27]
	v_mfma_f32_16x16x32_bf16 v[8:11], v[164:167], v[212:215], v[8:11]
	v_mfma_f32_16x16x32_bf16 v[12:15], v[156:159], v[212:215], v[12:15]
	s_setprio 0
	s_setprio 1
	v_mfma_f32_16x16x32_bf16 v[52:55], v[168:171], v[184:187], v[52:55]
	v_mfma_f32_16x16x32_bf16 v[48:51], v[176:179], v[184:187], v[48:51]
	v_mfma_f32_16x16x32_bf16 v[32:35], v[176:179], v[192:195], v[32:35]
	v_mfma_f32_16x16x32_bf16 v[36:39], v[168:171], v[192:195], v[36:39]
	v_mfma_f32_16x16x32_bf16 v[20:23], v[168:171], v[200:203], v[20:23]
	v_mfma_f32_16x16x32_bf16 v[16:19], v[176:179], v[200:203], v[16:19]
	v_mfma_f32_16x16x32_bf16 v[0:3], v[176:179], v[208:211], v[0:3]
	v_mfma_f32_16x16x32_bf16 v[4:7], v[168:171], v[208:211], v[4:7]
	v_mfma_f32_16x16x32_bf16 v[52:55], v[172:175], v[188:191], v[52:55]
	v_mfma_f32_16x16x32_bf16 v[48:51], v[180:183], v[188:191], v[48:51]
	v_mfma_f32_16x16x32_bf16 v[32:35], v[180:183], v[196:199], v[32:35]
	v_mfma_f32_16x16x32_bf16 v[36:39], v[172:175], v[196:199], v[36:39]
	v_mfma_f32_16x16x32_bf16 v[20:23], v[172:175], v[204:207], v[20:23]
	v_mfma_f32_16x16x32_bf16 v[16:19], v[180:183], v[204:207], v[16:19]
	v_mfma_f32_16x16x32_bf16 v[0:3], v[180:183], v[212:215], v[0:3]
	v_mfma_f32_16x16x32_bf16 v[4:7], v[172:175], v[212:215], v[4:7]
	s_setprio 0
	s_barrier
	s_add_i32 s66, 0, 0x18000
	v_add_u32_e32 v155, s66, v149
	s_add_i32 s67, 0, 0x1c000
	ds_read_b128 v[144:147], v155
	ds_read_b128 v[156:159], v155 offset:1024
	ds_read_b128 v[160:163], v155 offset:2048
	ds_read_b128 v[164:167], v155 offset:3072
	v_add_u32_e32 v155, s67, v149
	ds_read_b128 v[168:171], v155
	ds_read_b128 v[172:175], v155 offset:1024
	ds_read_b128 v[176:179], v155 offset:2048
	ds_read_b128 v[180:183], v155 offset:3072
	s_add_u32 s36, s36, 0x40000
	s_addc_u32 s37, s37, 0
	s_mov_b32 m0, s43
	v_lshl_add_u64 v[224:225], s[36:37], 0, v[134:135]
	ds_read_b128 v[184:187], v153 offset:32768
	ds_read_b128 v[188:191], v153 offset:33792
	ds_read_b128 v[192:195], v153 offset:34816
	ds_read_b128 v[196:199], v153 offset:35840
	ds_read_b128 v[200:203], v153 offset:36864
	ds_read_b128 v[204:207], v153 offset:37888
	ds_read_b128 v[208:211], v153 offset:38912
	ds_read_b128 v[212:215], v153 offset:39936
	global_load_lds_dwordx4 v[224:225], off
	v_lshl_add_u64 v[224:225], s[36:37], 0, v[130:131]
	s_mov_b32 m0, s46
	s_nop 0
	global_load_lds_dwordx4 v[224:225], off
	s_waitcnt vmcnt(8)
	s_waitcnt lgkmcnt(0)
	s_barrier
	s_setprio 1
	s_waitcnt lgkmcnt(0)
	v_mfma_f32_16x16x32_bf16 v[124:127], v[144:147], v[184:187], v[124:127]
	v_mfma_f32_16x16x32_bf16 v[120:123], v[160:163], v[184:187], v[120:123]
	v_mfma_f32_16x16x32_bf16 v[104:107], v[160:163], v[192:195], v[104:107]
	v_mfma_f32_16x16x32_bf16 v[108:111], v[144:147], v[192:195], v[108:111]
	v_mfma_f32_16x16x32_bf16 v[92:95], v[144:147], v[200:203], v[92:95]
	v_mfma_f32_16x16x32_bf16 v[88:91], v[160:163], v[200:203], v[88:91]
	v_mfma_f32_16x16x32_bf16 v[72:75], v[160:163], v[208:211], v[72:75]
	v_mfma_f32_16x16x32_bf16 v[76:79], v[144:147], v[208:211], v[76:79]
	v_mfma_f32_16x16x32_bf16 v[124:127], v[156:159], v[188:191], v[124:127]
	v_mfma_f32_16x16x32_bf16 v[120:123], v[164:167], v[188:191], v[120:123]
	v_mfma_f32_16x16x32_bf16 v[104:107], v[164:167], v[196:199], v[104:107]
	v_mfma_f32_16x16x32_bf16 v[108:111], v[156:159], v[196:199], v[108:111]
	v_mfma_f32_16x16x32_bf16 v[92:95], v[156:159], v[204:207], v[92:95]
	v_mfma_f32_16x16x32_bf16 v[88:91], v[164:167], v[204:207], v[88:91]
	v_mfma_f32_16x16x32_bf16 v[72:75], v[164:167], v[212:215], v[72:75]
	v_mfma_f32_16x16x32_bf16 v[76:79], v[156:159], v[212:215], v[76:79]
	s_setprio 0
	s_setprio 1
	v_mfma_f32_16x16x32_bf16 v[116:119], v[168:171], v[184:187], v[116:119]
	v_mfma_f32_16x16x32_bf16 v[112:115], v[176:179], v[184:187], v[112:115]
	v_mfma_f32_16x16x32_bf16 v[96:99], v[176:179], v[192:195], v[96:99]
	v_mfma_f32_16x16x32_bf16 v[100:103], v[168:171], v[192:195], v[100:103]
	v_mfma_f32_16x16x32_bf16 v[84:87], v[168:171], v[200:203], v[84:87]
	v_mfma_f32_16x16x32_bf16 v[80:83], v[176:179], v[200:203], v[80:83]
	v_mfma_f32_16x16x32_bf16 v[64:67], v[176:179], v[208:211], v[64:67]
	v_mfma_f32_16x16x32_bf16 v[68:71], v[168:171], v[208:211], v[68:71]
	v_mfma_f32_16x16x32_bf16 v[116:119], v[172:175], v[188:191], v[116:119]
	v_mfma_f32_16x16x32_bf16 v[112:115], v[180:183], v[188:191], v[112:115]
	v_mfma_f32_16x16x32_bf16 v[96:99], v[180:183], v[196:199], v[96:99]
	v_mfma_f32_16x16x32_bf16 v[100:103], v[172:175], v[196:199], v[100:103]
	v_mfma_f32_16x16x32_bf16 v[84:87], v[172:175], v[204:207], v[84:87]
	v_mfma_f32_16x16x32_bf16 v[80:83], v[180:183], v[204:207], v[80:83]
	v_mfma_f32_16x16x32_bf16 v[64:67], v[180:183], v[212:215], v[64:67]
	v_mfma_f32_16x16x32_bf16 v[68:71], v[172:175], v[212:215], v[68:71]
	s_setprio 0
	s_barrier
; #define PG8_STAGE(bufoff, gbase, voff) do { _Pragma("unroll") for (int _i = 0; _i < 2; ++_i) \
;         __builtin_amdgcn_global_load_lds((const unsigned*)((const char*)(gbase) + (voff)[_i]), (PG8_LAS unsigned*)(lds + (bufoff) + ldsw + _i * 8192), 16, 0, 0); } while (0)
; #define PG8_LDA(dst, b, h) do { _Pragma("unroll") for (int m = 0; m < 4; ++m) _Pragma("unroll") for (int k = 0; k < 2; ++k) dst[m][k] = *(const PG8_LAS bf16x8*)(lds + PG8_SA(b, h) + aoff + m * 2048 + k * 1024); } while (0)
; #define PG8_MMA(ai, bj, At, Bt) do { __builtin_amdgcn_s_setprio(1); _Pragma("unroll") for (int m = 0; m < 4; ++m) _Pragma("unroll") for (int n = 0; n < 2; ++n) _Pragma("unroll") for (int k = 0; k < 2; ++k) \
;         acc[ai][bj][m][n] = __builtin_amdgcn_mfma_f32_16x16x32_bf16(Bt[n][k], At[m][k], acc[ai][bj][m][n], 0, 0, 0); __builtin_amdgcn_s_setprio(0); } while (0)
; #define PG8_WAIT_V(n) asm volatile("s_waitcnt vmcnt(" #n ")" ::: "memory")
; #define PG8_WAIT_L(n) asm volatile("s_waitcnt lgkmcnt(" #n ")" ::: "memory")
; #define PG8_BAR __builtin_amdgcn_s_barrier()
; #define PG8_SCHED __builtin_amdgcn_sched_barrier(0)
; template <class Epi, class Sched, bool ALIGN_EPI = false, bool SP2 = false>
; __device__ __forceinline__ void gemm_phase(PG8_LAS unsigned char* lds, const Gemm g, const Sched& S, const Epi& E) {
;     ...
;             PG8_LDA(At, 1, 1); PG8_STAGE(PG8_SB(1, 0), b3, voffB); PG8_STAGE(PG8_SB(1, 1), b3 + hstep, voffB); PG8_STAGE(PG8_SA(1, 0), a3, voffA);
;             PG8_WAIT_V(8); PG8_WAIT_L(0); PG8_BAR; PG8_MMA(1, 0, At, B0); PG8_MMA(1, 1, At, B1); PG8_BAR; PG8_SCHED;
;     __device__ __forceinline__ void operator()(const f32x4 (&acc)[2][2][4][2], const Unit& u, int wr, int wc, int fr, int fq) const {
;     ...
;             for (int m = 0; m < 4; ++m) { const int row = rbase + ai * 128 + m * 16; const f32x4* sp = (const f32x4*)(SSP + (size_t)row * 16);
;                 const f32x4 s4 = (sp[0] + sp[1]) + (sp[2] + sp[3]); const float rstd = __builtin_amdgcn_rsqf(((s4[0] + s4[1]) + (s4[2] + s4[3])) * (1.0f / 1024.0f) + EPS);
	s_add_i32 s36, s66, s39
	v_lshl_add_u64 v[216:217], v[216:217], 0, s[14:15]
	s_mov_b32 m0, s36
	ds_read_b128 v[184:187], v153 offset:49152
	ds_read_b128 v[188:191], v153 offset:50176
	ds_read_b128 v[192:195], v153 offset:51200
	ds_read_b128 v[196:199], v153 offset:52224
	ds_read_b128 v[200:203], v153 offset:53248
	ds_read_b128 v[204:207], v153 offset:54272
	ds_read_b128 v[208:211], v153 offset:55296
	ds_read_b128 v[212:215], v153 offset:56320
	global_load_lds_dwordx4 v[216:217], off
	s_add_i32 m0, s36, 0x2000
	s_add_u32 s34, s34, 0x40080
	v_lshl_add_u64 v[216:217], v[218:219], 0, s[14:15]
	s_addc_u32 s35, s35, 0
	s_add_i32 s36, s67, s39
	global_load_lds_dwordx4 v[216:217], off
	v_lshl_add_u64 v[216:217], s[34:35], 0, v[132:133]
	s_mov_b32 m0, s36
	s_nop 0
	global_load_lds_dwordx4 v[216:217], off
	v_lshl_add_u64 v[216:217], s[34:35], 0, v[128:129]
	s_add_i32 m0, s36, 0x2000
	s_nop 0
	global_load_lds_dwordx4 v[216:217], off
	v_lshl_add_u64 v[216:217], v[220:221], 0, s[14:15]
	s_mov_b32 m0, s49
	s_nop 0
	global_load_lds_dwordx4 v[216:217], off
	v_lshl_add_u64 v[216:217], v[222:223], 0, s[14:15]
	s_mov_b32 m0, s50
	s_nop 0
	global_load_lds_dwordx4 v[216:217], off
	s_waitcnt vmcnt(8)
	s_waitcnt lgkmcnt(0)
	s_barrier
	s_setprio 1
	s_waitcnt lgkmcnt(0)
	v_mfma_f32_16x16x32_bf16 v[60:63], v[144:147], v[184:187], v[60:63]
	v_mfma_f32_16x16x32_bf16 v[56:59], v[160:163], v[184:187], v[56:59]
	v_mfma_f32_16x16x32_bf16 v[40:43], v[160:163], v[192:195], v[40:43]
	v_mfma_f32_16x16x32_bf16 v[44:47], v[144:147], v[192:195], v[44:47]
	v_mfma_f32_16x16x32_bf16 v[28:31], v[144:147], v[200:203], v[28:31]
	v_mfma_f32_16x16x32_bf16 v[24:27], v[160:163], v[200:203], v[24:27]
	v_mfma_f32_16x16x32_bf16 v[8:11], v[160:163], v[208:211], v[8:11]
	v_mfma_f32_16x16x32_bf16 v[12:15], v[144:147], v[208:211], v[12:15]
	v_mfma_f32_16x16x32_bf16 v[60:63], v[156:159], v[188:191], v[60:63]
	v_mfma_f32_16x16x32_bf16 v[56:59], v[164:167], v[188:191], v[56:59]
	v_mfma_f32_16x16x32_bf16 v[40:43], v[164:167], v[196:199], v[40:43]
	v_mfma_f32_16x16x32_bf16 v[44:47], v[156:159], v[196:199], v[44:47]
	v_mfma_f32_16x16x32_bf16 v[28:31], v[156:159], v[204:207], v[28:31]
	v_mfma_f32_16x16x32_bf16 v[24:27], v[164:167], v[204:207], v[24:27]
	v_mfma_f32_16x16x32_bf16 v[8:11], v[164:167], v[212:215], v[8:11]
	v_mfma_f32_16x16x32_bf16 v[12:15], v[156:159], v[212:215], v[12:15]
	s_setprio 0
	s_setprio 1
	v_mfma_f32_16x16x32_bf16 v[52:55], v[168:171], v[184:187], v[52:55]
	v_mfma_f32_16x16x32_bf16 v[48:51], v[176:179], v[184:187], v[48:51]
	v_mfma_f32_16x16x32_bf16 v[32:35], v[176:179], v[192:195], v[32:35]
	v_mfma_f32_16x16x32_bf16 v[36:39], v[168:171], v[192:195], v[36:39]
	v_mfma_f32_16x16x32_bf16 v[20:23], v[168:171], v[200:203], v[20:23]
	v_mfma_f32_16x16x32_bf16 v[16:19], v[176:179], v[200:203], v[16:19]
	v_mfma_f32_16x16x32_bf16 v[0:3], v[176:179], v[208:211], v[0:3]
	v_mfma_f32_16x16x32_bf16 v[4:7], v[168:171], v[208:211], v[4:7]
	v_mfma_f32_16x16x32_bf16 v[52:55], v[172:175], v[188:191], v[52:55]
	v_mfma_f32_16x16x32_bf16 v[48:51], v[180:183], v[188:191], v[48:51]
	v_mfma_f32_16x16x32_bf16 v[32:35], v[180:183], v[196:199], v[32:35]
	v_mfma_f32_16x16x32_bf16 v[36:39], v[172:175], v[196:199], v[36:39]
	v_mfma_f32_16x16x32_bf16 v[20:23], v[172:175], v[204:207], v[20:23]
	v_mfma_f32_16x16x32_bf16 v[16:19], v[180:183], v[204:207], v[16:19]
	v_mfma_f32_16x16x32_bf16 v[0:3], v[180:183], v[212:215], v[0:3]
	v_mfma_f32_16x16x32_bf16 v[4:7], v[172:175], v[212:215], v[4:7]
	s_setprio 0
	s_barrier
	s_mov_b32 s99, 0
	s_add_i32 s65, s65, 2
	s_add_u32 s30, s30, 0x100
	s_addc_u32 s31, s31, 0
	s_add_u32 s63, s63, 0x100
	s_addc_u32 s64, s64, 0
	s_cmp_gt_u32 s65, 13
	s_cbranch_scc0 .LBB0_1540
	v_lshl_add_u32 v146, s28, 8, v148
	v_ashrrev_i32_e32 v147, 31, v146
	v_lshlrev_b64 v[144:145], 6, v[146:147]
	v_lshl_add_u64 v[144:145], s[12:13], 0, v[144:145]
	global_load_dwordx4 v[156:159], v[144:145], off
	global_load_dwordx4 v[160:163], v[144:145], off offset:16
	global_load_dwordx4 v[164:167], v[144:145], off offset:32
	global_load_dwordx4 v[168:171], v[144:145], off offset:48
	global_load_dwordx4 v[172:175], v[144:145], off offset:1024
	global_load_dwordx4 v[176:179], v[144:145], off offset:1040
	global_load_dwordx4 v[180:183], v[144:145], off offset:1056
	global_load_dwordx4 v[184:187], v[144:145], off offset:1072
	global_load_dwordx4 v[188:191], v[144:145], off offset:2048
	global_load_dwordx4 v[192:195], v[144:145], off offset:2064
	global_load_dwordx4 v[196:199], v[144:145], off offset:2080
	global_load_dwordx4 v[200:203], v[144:145], off offset:2096
	global_load_dwordx4 v[204:207], v[144:145], off offset:3072
	global_load_dwordx4 v[208:211], v[144:145], off offset:3088
	global_load_dwordx4 v[212:215], v[144:145], off offset:3104
	global_load_dwordx4 v[216:219], v[144:145], off offset:3120
	s_and_b64 vcc, exec, s[16:17]
	s_cbranch_vccz .LBB0_1543
	s_barrier

; #define PG8_STAGE(bufoff, gbase, voff) do { _Pragma("unroll") for (int _i = 0; _i < 2; ++_i) \
;         __builtin_amdgcn_global_load_lds((const unsigned*)((const char*)(gbase) + (voff)[_i]), (PG8_LAS unsigned*)(lds + (bufoff) + ldsw + _i * 8192), 16, 0, 0); } while (0)
; #define PG8_LDA(dst, b, h) do { _Pragma("unroll") for (int m = 0; m < 4; ++m) _Pragma("unroll") for (int k = 0; k < 2; ++k) dst[m][k] = *(const PG8_LAS bf16x8*)(lds + PG8_SA(b, h) + aoff + m * 2048 + k * 1024); } while (0)
; #define PG8_MMA(ai, bj, At, Bt) do { __builtin_amdgcn_s_setprio(1); _Pragma("unroll") for (int m = 0; m < 4; ++m) _Pragma("unroll") for (int n = 0; n < 2; ++n) _Pragma("unroll") for (int k = 0; k < 2; ++k) \
;         acc[ai][bj][m][n] = __builtin_amdgcn_mfma_f32_16x16x32_bf16(Bt[n][k], At[m][k], acc[ai][bj][m][n], 0, 0, 0); __builtin_amdgcn_s_setprio(0); } while (0)
; #define PG8_WAIT_V(n) asm volatile("s_waitcnt vmcnt(" #n ")" ::: "memory")
; #define PG8_WAIT_L(n) asm volatile("s_waitcnt lgkmcnt(" #n ")" ::: "memory")
; #define PG8_BAR __builtin_amdgcn_s_barrier()
; #define PG8_SCHED __builtin_amdgcn_sched_barrier(0)
; template <class Epi, class Sched, bool ALIGN_EPI = false, bool SP2 = false>
; __device__ __forceinline__ void gemm_phase(PG8_LAS unsigned char* lds, const Gemm g, const Sched& S, const Epi& E) {
;     ...
;             PG8_WAIT_V(8); PG8_WAIT_L(0); PG8_BAR; PG8_MMA(0, 0, At, B0); PG8_MMA(0, 1, At, B1); PG8_BAR; PG8_SCHED;
;             PG8_LDA(At, 0, 1); PG8_STAGE(PG8_SB(0, 0), b2, voffB); PG8_STAGE(PG8_SB(0, 1), b2 + hstep, voffB); PG8_STAGE(PG8_SA(0, 0), a2, voffA);
.Lrj_P6_0:
	s_waitcnt lgkmcnt(0)
	s_barrier
	s_setprio 1
	s_waitcnt lgkmcnt(0)
	v_mfma_f32_16x16x32_bf16 v[124:127], v[152:155], v[184:187], v[124:127]
	v_mfma_f32_16x16x32_bf16 v[120:123], v[160:163], v[184:187], v[120:123]
	v_mfma_f32_16x16x32_bf16 v[104:107], v[160:163], v[192:195], v[104:107]
	v_mfma_f32_16x16x32_bf16 v[108:111], v[152:155], v[192:195], v[108:111]
	v_mfma_f32_16x16x32_bf16 v[92:95], v[152:155], v[200:203], v[92:95]
	v_mfma_f32_16x16x32_bf16 v[88:91], v[160:163], v[200:203], v[88:91]
	v_mfma_f32_16x16x32_bf16 v[72:75], v[160:163], v[208:211], v[72:75]
	v_mfma_f32_16x16x32_bf16 v[76:79], v[152:155], v[208:211], v[76:79]
	v_mfma_f32_16x16x32_bf16 v[124:127], v[156:159], v[188:191], v[124:127]
	v_mfma_f32_16x16x32_bf16 v[120:123], v[164:167], v[188:191], v[120:123]
	v_mfma_f32_16x16x32_bf16 v[104:107], v[164:167], v[196:199], v[104:107]
	v_mfma_f32_16x16x32_bf16 v[108:111], v[156:159], v[196:199], v[108:111]
	v_mfma_f32_16x16x32_bf16 v[92:95], v[156:159], v[204:207], v[92:95]
	v_mfma_f32_16x16x32_bf16 v[88:91], v[164:167], v[204:207], v[88:91]
	v_mfma_f32_16x16x32_bf16 v[72:75], v[164:167], v[212:215], v[72:75]
	v_mfma_f32_16x16x32_bf16 v[76:79], v[156:159], v[212:215], v[76:79]
	s_setprio 0
	s_setprio 1
	v_mfma_f32_16x16x32_bf16 v[116:119], v[168:171], v[184:187], v[116:119]
	v_mfma_f32_16x16x32_bf16 v[112:115], v[176:179], v[184:187], v[112:115]
	v_mfma_f32_16x16x32_bf16 v[96:99], v[176:179], v[192:195], v[96:99]
	v_mfma_f32_16x16x32_bf16 v[100:103], v[168:171], v[192:195], v[100:103]
	v_mfma_f32_16x16x32_bf16 v[84:87], v[168:171], v[200:203], v[84:87]
	v_mfma_f32_16x16x32_bf16 v[80:83], v[176:179], v[200:203], v[80:83]
	v_mfma_f32_16x16x32_bf16 v[64:67], v[176:179], v[208:211], v[64:67]
	v_mfma_f32_16x16x32_bf16 v[68:71], v[168:171], v[208:211], v[68:71]
	v_mfma_f32_16x16x32_bf16 v[116:119], v[172:175], v[188:191], v[116:119]
	v_mfma_f32_16x16x32_bf16 v[112:115], v[180:183], v[188:191], v[112:115]
	v_mfma_f32_16x16x32_bf16 v[96:99], v[180:183], v[196:199], v[96:99]
	v_mfma_f32_16x16x32_bf16 v[100:103], v[172:175], v[196:199], v[100:103]
	v_mfma_f32_16x16x32_bf16 v[84:87], v[172:175], v[204:207], v[84:87]
	v_mfma_f32_16x16x32_bf16 v[80:83], v[180:183], v[204:207], v[80:83]
	v_mfma_f32_16x16x32_bf16 v[64:67], v[180:183], v[212:215], v[64:67]
	v_mfma_f32_16x16x32_bf16 v[68:71], v[172:175], v[212:215], v[68:71]
	s_setprio 0
	s_barrier
	s_add_i32 s69, s51, s39
	v_lshl_add_u64 v[144:145], s[30:31], 0, v[132:133]
	s_mov_b32 m0, s69
	ds_read_b128 v[184:187], v151 offset:16384
	ds_read_b128 v[188:191], v151 offset:17408
	ds_read_b128 v[192:195], v151 offset:18432
	ds_read_b128 v[196:199], v151 offset:19456
	ds_read_b128 v[200:203], v151 offset:20480
	ds_read_b128 v[204:207], v151 offset:21504
	ds_read_b128 v[208:211], v151 offset:22528
	ds_read_b128 v[212:215], v151 offset:23552
	global_load_lds_dwordx4 v[144:145], off
	s_add_i32 m0, s69, 0x2000
	s_add_u32 s70, s30, 0x100000
	v_lshl_add_u64 v[216:217], s[30:31], 0, v[128:129]
	s_addc_u32 s71, s31, 0
	s_add_i32 s69, s52, s39
	global_load_lds_dwordx4 v[216:217], off
	v_lshl_add_u64 v[218:219], s[70:71], 0, v[132:133]
	s_mov_b32 m0, s69
	v_lshl_add_u64 v[220:221], s[34:35], 0, v[130:131]
	global_load_lds_dwordx4 v[218:219], off
	v_lshl_add_u64 v[218:219], s[70:71], 0, v[128:129]
	s_add_i32 m0, s69, 0x2000
	s_nop 0
	global_load_lds_dwordx4 v[218:219], off
	v_lshl_add_u64 v[218:219], s[34:35], 0, v[134:135]
	s_mov_b32 m0, s27
	s_nop 0
	global_load_lds_dwordx4 v[218:219], off
	s_mov_b32 m0, s42
	s_nop 0
	global_load_lds_dwordx4 v[220:221], off
	s_cmp_eq_u32 s99, 1
	s_cbranch_scc1 .Lrw_P6_1
	s_waitcnt vmcnt(8)
	s_branch .Lrj_P6_1

; #define PG8_STAGE(bufoff, gbase, voff) do { _Pragma("unroll") for (int _i = 0; _i < 2; ++_i) \
;         __builtin_amdgcn_global_load_lds((const unsigned*)((const char*)(gbase) + (voff)[_i]), (PG8_LAS unsigned*)(lds + (bufoff) + ldsw + _i * 8192), 16, 0, 0); } while (0)
; #define PG8_LDA(dst, b, h) do { _Pragma("unroll") for (int m = 0; m < 4; ++m) _Pragma("unroll") for (int k = 0; k < 2; ++k) dst[m][k] = *(const PG8_LAS bf16x8*)(lds + PG8_SA(b, h) + aoff + m * 2048 + k * 1024); } while (0)
; #define PG8_LDB(dst, b, h) do { _Pragma("unroll") for (int n = 0; n < 2; ++n) _Pragma("unroll") for (int k = 0; k < 2; ++k) dst[n][k] = *(const PG8_LAS bf16x8*)(lds + PG8_SB(b, h) + boff + n * 2048 + k * 1024); } while (0)
; #define PG8_MMA(ai, bj, At, Bt) do { __builtin_amdgcn_s_setprio(1); _Pragma("unroll") for (int m = 0; m < 4; ++m) _Pragma("unroll") for (int n = 0; n < 2; ++n) _Pragma("unroll") for (int k = 0; k < 2; ++k) \
;         acc[ai][bj][m][n] = __builtin_amdgcn_mfma_f32_16x16x32_bf16(Bt[n][k], At[m][k], acc[ai][bj][m][n], 0, 0, 0); __builtin_amdgcn_s_setprio(0); } while (0)
; #define PG8_WAIT_V(n) asm volatile("s_waitcnt vmcnt(" #n ")" ::: "memory")
; #define PG8_WAIT_L(n) asm volatile("s_waitcnt lgkmcnt(" #n ")" ::: "memory")
; #define PG8_BAR __builtin_amdgcn_s_barrier()
; #define PG8_SCHED __builtin_amdgcn_sched_barrier(0)
; template <class Epi, class Sched, bool ALIGN_EPI = false, bool SP2 = false>
; __device__ __forceinline__ void gemm_phase(PG8_LAS unsigned char* lds, const Gemm g, const Sched& S, const Epi& E) {
;     ...
;             PG8_WAIT_V(8); PG8_WAIT_L(0); PG8_BAR; PG8_MMA(1, 0, At, B0); PG8_MMA(1, 1, At, B1); PG8_BAR; PG8_SCHED;
;             PG8_LDB(B0, 1, 0); PG8_LDB(B1, 1, 1); PG8_SCHED; PG8_LDA(At, 1, 0); PG8_STAGE(PG8_SA(0, 1), a2 + hstep, voffA);
;             PG8_WAIT_V(8); PG8_WAIT_L(0); PG8_BAR; PG8_MMA(0, 0, At, B0); PG8_MMA(0, 1, At, B1); PG8_BAR; PG8_SCHED;
.Lrj_P6_1:
	s_waitcnt lgkmcnt(0)
	s_barrier
	s_setprio 1
	s_waitcnt lgkmcnt(0)
	v_mfma_f32_16x16x32_bf16 v[60:63], v[152:155], v[184:187], v[60:63]
	v_mfma_f32_16x16x32_bf16 v[56:59], v[160:163], v[184:187], v[56:59]
	v_mfma_f32_16x16x32_bf16 v[40:43], v[160:163], v[192:195], v[40:43]
	v_mfma_f32_16x16x32_bf16 v[44:47], v[152:155], v[192:195], v[44:47]
	v_mfma_f32_16x16x32_bf16 v[28:31], v[152:155], v[200:203], v[28:31]
	v_mfma_f32_16x16x32_bf16 v[24:27], v[160:163], v[200:203], v[24:27]
	v_mfma_f32_16x16x32_bf16 v[8:11], v[160:163], v[208:211], v[8:11]
	v_mfma_f32_16x16x32_bf16 v[12:15], v[152:155], v[208:211], v[12:15]
	v_mfma_f32_16x16x32_bf16 v[60:63], v[156:159], v[188:191], v[60:63]
	v_mfma_f32_16x16x32_bf16 v[56:59], v[164:167], v[188:191], v[56:59]
	v_mfma_f32_16x16x32_bf16 v[40:43], v[164:167], v[196:199], v[40:43]
	v_mfma_f32_16x16x32_bf16 v[44:47], v[156:159], v[196:199], v[44:47]
	v_mfma_f32_16x16x32_bf16 v[28:31], v[156:159], v[204:207], v[28:31]
	v_mfma_f32_16x16x32_bf16 v[24:27], v[164:167], v[204:207], v[24:27]
	v_mfma_f32_16x16x32_bf16 v[8:11], v[164:167], v[212:215], v[8:11]
	v_mfma_f32_16x16x32_bf16 v[12:15], v[156:159], v[212:215], v[12:15]
	s_setprio 0
	s_setprio 1
	v_mfma_f32_16x16x32_bf16 v[52:55], v[168:171], v[184:187], v[52:55]
	v_mfma_f32_16x16x32_bf16 v[48:51], v[176:179], v[184:187], v[48:51]
	v_mfma_f32_16x16x32_bf16 v[32:35], v[176:179], v[192:195], v[32:35]
	v_mfma_f32_16x16x32_bf16 v[36:39], v[168:171], v[192:195], v[36:39]
	v_mfma_f32_16x16x32_bf16 v[20:23], v[168:171], v[200:203], v[20:23]
	v_mfma_f32_16x16x32_bf16 v[16:19], v[176:179], v[200:203], v[16:19]
	v_mfma_f32_16x16x32_bf16 v[0:3], v[176:179], v[208:211], v[0:3]
	v_mfma_f32_16x16x32_bf16 v[4:7], v[168:171], v[208:211], v[4:7]
	v_mfma_f32_16x16x32_bf16 v[52:55], v[172:175], v[188:191], v[52:55]
	v_mfma_f32_16x16x32_bf16 v[48:51], v[180:183], v[188:191], v[48:51]
	v_mfma_f32_16x16x32_bf16 v[32:35], v[180:183], v[196:199], v[32:35]
	v_mfma_f32_16x16x32_bf16 v[36:39], v[172:175], v[196:199], v[36:39]
	v_mfma_f32_16x16x32_bf16 v[20:23], v[172:175], v[204:207], v[20:23]
	v_mfma_f32_16x16x32_bf16 v[16:19], v[180:183], v[204:207], v[16:19]
	v_mfma_f32_16x16x32_bf16 v[0:3], v[180:183], v[212:215], v[0:3]
	v_mfma_f32_16x16x32_bf16 v[4:7], v[172:175], v[212:215], v[4:7]
	s_setprio 0
	s_barrier
	s_add_i32 s69, 0, 0x18000
	s_add_i32 s70, 0, 0x1c000
	v_add_u32_e32 v164, s69, v147
	v_add_u32_e32 v180, s70, v147
	ds_read_b128 v[152:155], v164
	ds_read_b128 v[156:159], v164 offset:1024
	ds_read_b128 v[160:163], v164 offset:2048
	ds_read_b128 v[164:167], v164 offset:3072
	ds_read_b128 v[168:171], v180
	ds_read_b128 v[172:175], v180 offset:1024
	ds_read_b128 v[176:179], v180 offset:2048
	ds_read_b128 v[180:183], v180 offset:3072
	s_add_u32 s34, s34, 0x100000
	s_addc_u32 s35, s35, 0
	s_mov_b32 m0, s43
	v_lshl_add_u64 v[222:223], s[34:35], 0, v[134:135]
	ds_read_b128 v[184:187], v151 offset:32768
	ds_read_b128 v[188:191], v151 offset:33792
	ds_read_b128 v[192:195], v151 offset:34816
	ds_read_b128 v[196:199], v151 offset:35840
	ds_read_b128 v[200:203], v151 offset:36864
	ds_read_b128 v[204:207], v151 offset:37888
	ds_read_b128 v[208:211], v151 offset:38912
	ds_read_b128 v[212:215], v151 offset:39936
	global_load_lds_dwordx4 v[222:223], off
	v_lshl_add_u64 v[222:223], s[34:35], 0, v[130:131]
	s_mov_b32 m0, s46
	s_nop 0
	global_load_lds_dwordx4 v[222:223], off
	s_waitcnt vmcnt(8)
	s_waitcnt lgkmcnt(0)
	s_barrier
	s_setprio 1
	s_waitcnt lgkmcnt(0)
	v_mfma_f32_16x16x32_bf16 v[124:127], v[152:155], v[184:187], v[124:127]
	v_mfma_f32_16x16x32_bf16 v[120:123], v[160:163], v[184:187], v[120:123]
	v_mfma_f32_16x16x32_bf16 v[104:107], v[160:163], v[192:195], v[104:107]
	v_mfma_f32_16x16x32_bf16 v[108:111], v[152:155], v[192:195], v[108:111]
	v_mfma_f32_16x16x32_bf16 v[92:95], v[152:155], v[200:203], v[92:95]
	v_mfma_f32_16x16x32_bf16 v[88:91], v[160:163], v[200:203], v[88:91]
	v_mfma_f32_16x16x32_bf16 v[72:75], v[160:163], v[208:211], v[72:75]
	v_mfma_f32_16x16x32_bf16 v[76:79], v[152:155], v[208:211], v[76:79]
	v_mfma_f32_16x16x32_bf16 v[124:127], v[156:159], v[188:191], v[124:127]
	v_mfma_f32_16x16x32_bf16 v[120:123], v[164:167], v[188:191], v[120:123]
	v_mfma_f32_16x16x32_bf16 v[104:107], v[164:167], v[196:199], v[104:107]
	v_mfma_f32_16x16x32_bf16 v[108:111], v[156:159], v[196:199], v[108:111]
	v_mfma_f32_16x16x32_bf16 v[92:95], v[156:159], v[204:207], v[92:95]
	v_mfma_f32_16x16x32_bf16 v[88:91], v[164:167], v[204:207], v[88:91]
	v_mfma_f32_16x16x32_bf16 v[72:75], v[164:167], v[212:215], v[72:75]
	v_mfma_f32_16x16x32_bf16 v[76:79], v[156:159], v[212:215], v[76:79]
	s_setprio 0
	s_setprio 1
	v_mfma_f32_16x16x32_bf16 v[116:119], v[168:171], v[184:187], v[116:119]
	v_mfma_f32_16x16x32_bf16 v[112:115], v[176:179], v[184:187], v[112:115]
	v_mfma_f32_16x16x32_bf16 v[96:99], v[176:179], v[192:195], v[96:99]
	v_mfma_f32_16x16x32_bf16 v[100:103], v[168:171], v[192:195], v[100:103]
	v_mfma_f32_16x16x32_bf16 v[84:87], v[168:171], v[200:203], v[84:87]
	v_mfma_f32_16x16x32_bf16 v[80:83], v[176:179], v[200:203], v[80:83]
	v_mfma_f32_16x16x32_bf16 v[64:67], v[176:179], v[208:211], v[64:67]
	v_mfma_f32_16x16x32_bf16 v[68:71], v[168:171], v[208:211], v[68:71]
	v_mfma_f32_16x16x32_bf16 v[116:119], v[172:175], v[188:191], v[116:119]
	v_mfma_f32_16x16x32_bf16 v[112:115], v[180:183], v[188:191], v[112:115]
	v_mfma_f32_16x16x32_bf16 v[96:99], v[180:183], v[196:199], v[96:99]
	v_mfma_f32_16x16x32_bf16 v[100:103], v[172:175], v[196:199], v[100:103]
	v_mfma_f32_16x16x32_bf16 v[84:87], v[172:175], v[204:207], v[84:87]
	v_mfma_f32_16x16x32_bf16 v[80:83], v[180:183], v[204:207], v[80:83]
	v_mfma_f32_16x16x32_bf16 v[64:67], v[180:183], v[212:215], v[64:67]
	v_mfma_f32_16x16x32_bf16 v[68:71], v[172:175], v[212:215], v[68:71]
	s_setprio 0
	s_barrier
; #define PG8_STAGE(bufoff, gbase, voff) do { _Pragma("unroll") for (int _i = 0; _i < 2; ++_i) \
;         __builtin_amdgcn_global_load_lds((const unsigned*)((const char*)(gbase) + (voff)[_i]), (PG8_LAS unsigned*)(lds + (bufoff) + ldsw + _i * 8192), 16, 0, 0); } while (0)
; #define PG8_LDA(dst, b, h) do { _Pragma("unroll") for (int m = 0; m < 4; ++m) _Pragma("unroll") for (int k = 0; k < 2; ++k) dst[m][k] = *(const PG8_LAS bf16x8*)(lds + PG8_SA(b, h) + aoff + m * 2048 + k * 1024); } while (0)
; #define PG8_MMA(ai, bj, At, Bt) do { __builtin_amdgcn_s_setprio(1); _Pragma("unroll") for (int m = 0; m < 4; ++m) _Pragma("unroll") for (int n = 0; n < 2; ++n) _Pragma("unroll") for (int k = 0; k < 2; ++k) \
;         acc[ai][bj][m][n] = __builtin_amdgcn_mfma_f32_16x16x32_bf16(Bt[n][k], At[m][k], acc[ai][bj][m][n], 0, 0, 0); __builtin_amdgcn_s_setprio(0); } while (0)
; #define PG8_WAIT_V(n) asm volatile("s_waitcnt vmcnt(" #n ")" ::: "memory")
; #define PG8_WAIT_L(n) asm volatile("s_waitcnt lgkmcnt(" #n ")" ::: "memory")
; #define PG8_BAR __builtin_amdgcn_s_barrier()
; #define PG8_SCHED __builtin_amdgcn_sched_barrier(0)
; template <class Epi, class Sched, bool ALIGN_EPI = false, bool SP2 = false>
; __device__ __forceinline__ void gemm_phase(PG8_LAS unsigned char* lds, const Gemm g, const Sched& S, const Epi& E) {
;     ...
;             PG8_LDA(At, 1, 1); PG8_STAGE(PG8_SB(1, 0), b3, voffB); PG8_STAGE(PG8_SB(1, 1), b3 + hstep, voffB); PG8_STAGE(PG8_SA(1, 0), a3, voffA);
;             PG8_WAIT_V(8); PG8_WAIT_L(0); PG8_BAR; PG8_MMA(1, 0, At, B0); PG8_MMA(1, 1, At, B1); PG8_BAR; PG8_SCHED;
;     __device__ __forceinline__ void operator()(const f32x4 (&acc)[2][2][4][2], const Unit& u, int wr, int wc, int fr, int fq) const {
;     ...
;             for (int m = 0; m < 4; ++m) { float* yr = y + (size_t)(rbase + ai * 128 + m * 16) * 1024 + cb;
; #pragma unroll
;                 for (int bj = 0; bj < 2; ++bj) { float* yp = yr + bj * 128; const f32x4 a = *(const f32x4*)yp + acc[ai][bj][m][0], b = *(const f32x4*)(yp + 4) + acc[ai][bj][m][1]; *(f32x4*)yp = a; *(f32x4*)(yp + 4) = b; }
	s_add_i32 s34, s69, s39
	v_lshl_add_u64 v[144:145], v[144:145], 0, s[6:7]
	s_mov_b32 m0, s34
	ds_read_b128 v[184:187], v151 offset:49152
	ds_read_b128 v[188:191], v151 offset:50176
	ds_read_b128 v[192:195], v151 offset:51200
	ds_read_b128 v[196:199], v151 offset:52224
	ds_read_b128 v[200:203], v151 offset:53248
	ds_read_b128 v[204:207], v151 offset:54272
	ds_read_b128 v[208:211], v151 offset:55296
	ds_read_b128 v[212:215], v151 offset:56320
	global_load_lds_dwordx4 v[144:145], off
	s_add_i32 m0, s34, 0x2000
	s_add_u32 s30, s30, 0x100080
	v_lshl_add_u64 v[144:145], v[216:217], 0, s[6:7]
	s_addc_u32 s31, s31, 0
	s_add_i32 s34, s70, s39
	global_load_lds_dwordx4 v[144:145], off
	v_lshl_add_u64 v[144:145], s[30:31], 0, v[132:133]
	s_mov_b32 m0, s34
	s_nop 0
	global_load_lds_dwordx4 v[144:145], off
	v_lshl_add_u64 v[144:145], s[30:31], 0, v[128:129]
	s_add_i32 m0, s34, 0x2000
	s_nop 0
	global_load_lds_dwordx4 v[144:145], off
	v_lshl_add_u64 v[144:145], v[218:219], 0, s[6:7]
	s_mov_b32 m0, s48
	s_nop 0
	global_load_lds_dwordx4 v[144:145], off
	v_lshl_add_u64 v[144:145], v[220:221], 0, s[6:7]
	s_mov_b32 m0, s49
	s_nop 0
	global_load_lds_dwordx4 v[144:145], off
	s_waitcnt vmcnt(8)
	s_waitcnt lgkmcnt(0)
	s_barrier
	s_setprio 1
	s_waitcnt lgkmcnt(0)
	v_mfma_f32_16x16x32_bf16 v[60:63], v[152:155], v[184:187], v[60:63]
	v_mfma_f32_16x16x32_bf16 v[56:59], v[160:163], v[184:187], v[56:59]
	v_mfma_f32_16x16x32_bf16 v[40:43], v[160:163], v[192:195], v[40:43]
	v_mfma_f32_16x16x32_bf16 v[44:47], v[152:155], v[192:195], v[44:47]
	v_mfma_f32_16x16x32_bf16 v[28:31], v[152:155], v[200:203], v[28:31]
	v_mfma_f32_16x16x32_bf16 v[24:27], v[160:163], v[200:203], v[24:27]
	v_mfma_f32_16x16x32_bf16 v[8:11], v[160:163], v[208:211], v[8:11]
	v_mfma_f32_16x16x32_bf16 v[12:15], v[152:155], v[208:211], v[12:15]
	v_mfma_f32_16x16x32_bf16 v[60:63], v[156:159], v[188:191], v[60:63]
	v_mfma_f32_16x16x32_bf16 v[56:59], v[164:167], v[188:191], v[56:59]
	v_mfma_f32_16x16x32_bf16 v[40:43], v[164:167], v[196:199], v[40:43]
	v_mfma_f32_16x16x32_bf16 v[44:47], v[156:159], v[196:199], v[44:47]
	v_mfma_f32_16x16x32_bf16 v[28:31], v[156:159], v[204:207], v[28:31]
	v_mfma_f32_16x16x32_bf16 v[24:27], v[164:167], v[204:207], v[24:27]
	v_mfma_f32_16x16x32_bf16 v[8:11], v[164:167], v[212:215], v[8:11]
	v_mfma_f32_16x16x32_bf16 v[12:15], v[156:159], v[212:215], v[12:15]
	s_setprio 0
	s_setprio 1
	v_mfma_f32_16x16x32_bf16 v[52:55], v[168:171], v[184:187], v[52:55]
	v_mfma_f32_16x16x32_bf16 v[48:51], v[176:179], v[184:187], v[48:51]
	v_mfma_f32_16x16x32_bf16 v[32:35], v[176:179], v[192:195], v[32:35]
	v_mfma_f32_16x16x32_bf16 v[36:39], v[168:171], v[192:195], v[36:39]
	v_mfma_f32_16x16x32_bf16 v[20:23], v[168:171], v[200:203], v[20:23]
	v_mfma_f32_16x16x32_bf16 v[16:19], v[176:179], v[200:203], v[16:19]
	v_mfma_f32_16x16x32_bf16 v[0:3], v[176:179], v[208:211], v[0:3]
	v_mfma_f32_16x16x32_bf16 v[4:7], v[168:171], v[208:211], v[4:7]
	v_mfma_f32_16x16x32_bf16 v[52:55], v[172:175], v[188:191], v[52:55]
	v_mfma_f32_16x16x32_bf16 v[48:51], v[180:183], v[188:191], v[48:51]
	v_mfma_f32_16x16x32_bf16 v[32:35], v[180:183], v[196:199], v[32:35]
	v_mfma_f32_16x16x32_bf16 v[36:39], v[172:175], v[196:199], v[36:39]
	v_mfma_f32_16x16x32_bf16 v[20:23], v[172:175], v[204:207], v[20:23]
	v_mfma_f32_16x16x32_bf16 v[16:19], v[180:183], v[204:207], v[16:19]
	v_mfma_f32_16x16x32_bf16 v[0:3], v[180:183], v[212:215], v[0:3]
	v_mfma_f32_16x16x32_bf16 v[4:7], v[172:175], v[212:215], v[4:7]
	s_setprio 0
	s_barrier
	s_mov_b32 s99, 0
	s_add_i32 s68, s68, 2
	s_add_u32 s28, s28, 0x100
	s_addc_u32 s29, s29, 0
	s_add_u32 s66, s66, 0x100
	s_addc_u32 s67, s67, 0
	s_cmp_gt_u32 s68, 61
	s_cbranch_scc0 .LBB0_2136
	v_and_b32_e32 v216, 0xfffffff7, v146
	v_lshl_add_u32 v216, s26, 8, v216
	v_bfe_u32 v220, v146, 3, 1
	v_lshl_add_u32 v220, v220, 2, v148
	v_lshl_or_b32 v220, s63, 8, v220
	v_ashrrev_i32_e32 v217, 31, v216
	v_ashrrev_i32_e32 v221, 31, v220
	v_lshlrev_b64 v[216:217], 12, v[216:217]
	v_lshlrev_b64 v[220:221], 2, v[220:221]
	v_lshl_add_u64 v[216:217], s[84:85], 0, v[216:217]
	v_lshl_add_u64 v[216:217], v[216:217], 0, v[220:221]
	s_mov_b64 s[98:99], 0x8000
	v_lshl_add_u64 v[218:219], v[216:217], 0, s[98:99]
	v_mov_b64_e32 v[220:221], v[216:217]
	v_mov_b64_e32 v[222:223], v[218:219]
	s_mov_b64 s[98:99], 0x10000
	s_mov_b64 s[100:101], 0x50000
	global_load_dwordx4 v[152:155], v[216:217], off
	global_load_dwordx4 v[156:159], v[218:219], off
	global_load_dwordx4 v[160:163], v[216:217], off offset:512
	global_load_dwordx4 v[164:167], v[218:219], off offset:512
	v_lshl_add_u64 v[216:217], v[216:217], 0, s[98:99]
	v_lshl_add_u64 v[218:219], v[218:219], 0, s[98:99]
	global_load_dwordx4 v[168:171], v[216:217], off
	global_load_dwordx4 v[172:175], v[218:219], off
	global_load_dwordx4 v[176:179], v[216:217], off offset:512
	global_load_dwordx4 v[180:183], v[218:219], off offset:512
	v_lshl_add_u64 v[216:217], v[216:217], 0, s[98:99]
	v_lshl_add_u64 v[218:219], v[218:219], 0, s[98:99]
	global_load_dwordx4 v[184:187], v[216:217], off
	global_load_dwordx4 v[188:191], v[218:219], off
	global_load_dwordx4 v[192:195], v[216:217], off offset:512
	global_load_dwordx4 v[196:199], v[218:219], off offset:512
	v_lshl_add_u64 v[216:217], v[216:217], 0, s[98:99]
	v_lshl_add_u64 v[218:219], v[218:219], 0, s[98:99]
	global_load_dwordx4 v[200:203], v[216:217], off
	global_load_dwordx4 v[204:207], v[218:219], off
	global_load_dwordx4 v[208:211], v[216:217], off offset:512
	global_load_dwordx4 v[212:215], v[218:219], off offset:512
	v_lshl_add_u64 v[216:217], v[216:217], 0, s[100:101]
	v_lshl_add_u64 v[218:219], v[218:219], 0, s[100:101]
	global_load_dwordx4 v[228:231], v[216:217], off
	global_load_dwordx4 v[232:235], v[218:219], off
	global_load_dwordx4 v[236:239], v[216:217], off offset:512
	global_load_dwordx4 v[240:243], v[218:219], off offset:512
	v_lshl_add_u64 v[216:217], v[216:217], 0, s[98:99]
	v_lshl_add_u64 v[218:219], v[218:219], 0, s[98:99]
	s_and_b64 vcc, exec, s[8:9]
	s_cbranch_vccz .LBB0_2139
	s_barrier
